# pass C LDS state image row stride 64->72 B (removes 16-way bank conflicts of the image writes)
# speedup vs baseline: 1.0573x; 1.0216x over previous
.LBB0_1386:
	s_or_b64 exec, exec, s[0:1]
	v_readlane_b32 s2, v255, 3
	v_readlane_b32 s3, v255, 4
	s_waitcnt lgkmcnt(0)
	v_mov_b32_e32 v2, v0
	v_readlane_b32 s0, v255, 7
	s_barrier
	s_cmpk_gt_i32 s0, 0x3ff
	v_readfirstlane_b32 s6, v2
	s_cbranch_scc1 .LBB0_1414
	s_cmp_eq_u32 s97, 0x100
	s_cbranch_scc0 .Lpc_compiled
	v_readlane_b32 s6, v255, 3
	v_readlane_b32 s7, v255, 4
	v_readlane_b32 s46, v255, 7
	v_readlane_b32 s47, v255, 2
	s_nop 4
	s_load_dwordx4 s[8:11], s[6:7], 0xc8
	s_load_dwordx2 s[12:13], s[6:7], 0xa0
	s_lshr_b32 s47, s47, 6
	s_mul_i32 s48, s47, 0x2400
	s_mov_b32 s42, -1
	s_mov_b32 s43, 0
	s_mov_b32 s44, 0xffff
	s_mov_b32 s45, 0xffff
	v_and_b32_e32 v209, 63, v0
	v_and_b32_e32 v210, 31, v209
	v_lshrrev_b32_e32 v211, 5, v209
	v_cmp_lt_u32_e64 s[40:41], 31, v209
	v_xor_b32_e32 v199, 32, v209
	v_lshlrev_b32_e32 v199, 2, v199
	v_mul_u32_u24_e32 v200, 0x48, v210
	v_lshl_add_u32 v200, v211, 3, v200
	v_add_u32_e32 v200, s48, v200
	v_and_b32_e32 v212, 15, v209
	v_lshrrev_b32_e32 v213, 2, v212
	v_and_b32_e32 v212, 3, v212
	v_bfe_u32 v214, v209, 4, 1
	v_lshl_add_u32 v213, v211, 3, v213
	v_mul_u32_u24_e32 v201, 0x48, v213
	v_lshl_add_u32 v212, v214, 2, v212
	v_lshl_add_u32 v201, v212, 3, v201
	v_add_u32_e32 v201, s48, v201
	v_lshlrev_b32_e32 v202, 2, v210
	v_lshl_add_u32 v202, v211, 8, v202
	v_add_u32_e32 v202, s48, v202
	v_lshrrev_b32_e32 v212, 1, v209
	v_and_b32_e32 v213, 1, v209
	v_lshlrev_b32_e32 v203, 6, v212
	v_lshl_add_u32 v203, v213, 5, v203
	v_add_u32_e32 v203, s48, v203
	v_lshlrev_b32_e32 v204, 12, v210
	v_lshl_add_u32 v204, v211, 4, v204
	v_lshlrev_b32_e32 v205, 12, v212
	v_lshl_add_u32 v205, v213, 4, v205
	v_lshlrev_b32_e32 v206, 2, v210
	v_lshlrev_b32_e32 v207, 3, v210
	v_lshlrev_b32_e32 v208, 4, v209
	v_lshlrev_b32_e32 v212, 3, v211
	v_sub_u32_e32 v212, v210, v212
	s_waitcnt lgkmcnt(0)
	v_mov_b32_e32 v254, v212
	v_cmp_gt_u32_e64 s[38:39], 16, v210

.Lpc_kq_done:
	s_waitcnt vmcnt(9)
	v_cndmask_b32_e64 v210, 0, v210, s[38:39]
	v_cvt_pk_bf16_f32 v210, v210, 0
	v_and_b32_e32 v210, 0xffff, v210
	v_and_b32_e32 v211, 1, v254
	v_lshlrev_b32_e32 v211, 4, v211
	v_lshlrev_b32_e32 v210, v211, v210
	v_ashrrev_i32_e32 v211, 1, v254
	v_cmp_eq_u32_e32 vcc, 0, v211
	s_nop 1
	v_cndmask_b32_e32 v42, 0, v210, vcc
	v_cmp_eq_u32_e32 vcc, 1, v211
	s_nop 1
	v_cndmask_b32_e32 v43, 0, v210, vcc
	v_cmp_eq_u32_e32 vcc, 2, v211
	s_nop 1
	v_cndmask_b32_e32 v44, 0, v210, vcc
	v_cmp_eq_u32_e32 vcc, 3, v211
	s_nop 1
	v_cndmask_b32_e32 v45, 0, v210, vcc
	s_waitcnt vmcnt(0)
	v_mfma_f32_32x32x16_bf16 v[46:61], v[126:129], v[26:29], 0
	v_mfma_f32_32x32x16_bf16 v[78:93], v[126:129], v[34:37], 0
	v_mfma_f32_32x32x16_bf16 v[62:77], v[126:129], v[30:33], 0
	v_mfma_f32_32x32x16_bf16 v[94:109], v[126:129], v[38:41], 0
	v_mfma_f32_32x32x16_bf16 v[110:125], v[126:129], v[42:45], 0
	s_add_u32 s70, s58, 0x20000
	s_addc_u32 s71, s59, 0
	global_load_dwordx4 v[130:133], v204, s[70:71]
	s_nop 7
	s_nop 1
	v_fmac_f32_e32 v47, v6, v46
	v_fmac_f32_e32 v79, v6, v78
	v_fma_f32 v47, -v7, v78, v47
	v_fmac_f32_e32 v79, v7, v46
	v_fmac_f32_e32 v51, v6, v50
	v_fmac_f32_e32 v83, v6, v82
	v_fma_f32 v51, -v7, v82, v51
	v_fmac_f32_e32 v83, v7, v50
	v_fmac_f32_e32 v55, v6, v54
	v_fmac_f32_e32 v87, v6, v86
	v_fma_f32 v55, -v7, v86, v55
	v_fmac_f32_e32 v87, v7, v54
	v_fmac_f32_e32 v59, v6, v58
	v_fmac_f32_e32 v91, v6, v90
	v_fma_f32 v59, -v7, v90, v59
	v_fmac_f32_e32 v91, v7, v58
	v_fmac_f32_e32 v63, v14, v62
	v_fmac_f32_e32 v95, v14, v94
	v_fma_f32 v63, -v15, v94, v63
	v_fmac_f32_e32 v95, v15, v62
	v_fmac_f32_e32 v67, v14, v66
	v_fmac_f32_e32 v99, v14, v98
	v_fma_f32 v67, -v15, v98, v67
	v_fmac_f32_e32 v99, v15, v66
	v_fmac_f32_e32 v71, v14, v70
	v_fmac_f32_e32 v103, v14, v102
	v_fma_f32 v71, -v15, v102, v71
	v_fmac_f32_e32 v103, v15, v70
	v_fmac_f32_e32 v75, v14, v74
	v_fmac_f32_e32 v107, v14, v106
	v_fma_f32 v75, -v15, v106, v75
	v_fmac_f32_e32 v107, v15, v74
	v_fmac_f32_e32 v48, v6, v47
	v_fmac_f32_e32 v80, v6, v79
	v_fma_f32 v48, -v7, v79, v48
	v_fmac_f32_e32 v80, v7, v47
	v_fmac_f32_e32 v52, v6, v51
	v_fmac_f32_e32 v84, v6, v83
	v_fma_f32 v52, -v7, v83, v52
	v_fmac_f32_e32 v84, v7, v51
	v_fmac_f32_e32 v56, v6, v55
	v_fmac_f32_e32 v88, v6, v87
	v_fma_f32 v56, -v7, v87, v56
	v_fmac_f32_e32 v88, v7, v55
	v_fmac_f32_e32 v60, v6, v59
	v_fmac_f32_e32 v92, v6, v91
	v_fma_f32 v60, -v7, v91, v60
	v_fmac_f32_e32 v92, v7, v59
	v_fmac_f32_e32 v64, v14, v63
	v_fmac_f32_e32 v96, v14, v95
	v_fma_f32 v64, -v15, v95, v64
	v_fmac_f32_e32 v96, v15, v63
	v_fmac_f32_e32 v68, v14, v67
	v_fmac_f32_e32 v100, v14, v99
	v_fma_f32 v68, -v15, v99, v68
	v_fmac_f32_e32 v100, v15, v67
	v_fmac_f32_e32 v72, v14, v71
	v_fmac_f32_e32 v104, v14, v103
	v_fma_f32 v72, -v15, v103, v72
	v_fmac_f32_e32 v104, v15, v71
	v_fmac_f32_e32 v76, v14, v75
	v_fmac_f32_e32 v108, v14, v107
	v_fma_f32 v76, -v15, v107, v76
	v_fmac_f32_e32 v108, v15, v75
	v_fmac_f32_e32 v49, v6, v48
	v_fmac_f32_e32 v81, v6, v80
	v_fma_f32 v49, -v7, v80, v49
	v_fmac_f32_e32 v81, v7, v48
	v_fmac_f32_e32 v53, v6, v52
	v_fmac_f32_e32 v85, v6, v84
	v_fma_f32 v53, -v7, v84, v53
	v_fmac_f32_e32 v85, v7, v52
	v_fmac_f32_e32 v57, v6, v56
	v_fmac_f32_e32 v89, v6, v88
	v_fma_f32 v57, -v7, v88, v57
	v_fmac_f32_e32 v89, v7, v56
	v_fmac_f32_e32 v61, v6, v60
	v_fmac_f32_e32 v93, v6, v92
	v_fma_f32 v61, -v7, v92, v61
	v_fmac_f32_e32 v93, v7, v60
	v_fmac_f32_e32 v65, v14, v64
	v_fmac_f32_e32 v97, v14, v96
	v_fma_f32 v65, -v15, v96, v65
	v_fmac_f32_e32 v97, v15, v64
	v_fmac_f32_e32 v69, v14, v68
	v_fmac_f32_e32 v101, v14, v100
	v_fma_f32 v69, -v15, v100, v69
	v_fmac_f32_e32 v101, v15, v68
	v_fmac_f32_e32 v73, v14, v72
	v_fmac_f32_e32 v105, v14, v104
	v_fma_f32 v73, -v15, v104, v73
	v_fmac_f32_e32 v105, v15, v72
	v_fmac_f32_e32 v77, v14, v76
	v_fmac_f32_e32 v109, v14, v108
	v_fma_f32 v77, -v15, v108, v77
	v_fmac_f32_e32 v109, v15, v76
	ds_bpermute_b32 v167, v199, v49
	ds_bpermute_b32 v168, v199, v81
	ds_bpermute_b32 v169, v199, v53
	ds_bpermute_b32 v170, v199, v85
	ds_bpermute_b32 v171, v199, v57
	ds_bpermute_b32 v172, v199, v89
	ds_bpermute_b32 v173, v199, v61
	ds_bpermute_b32 v174, v199, v93
	ds_bpermute_b32 v175, v199, v65
	ds_bpermute_b32 v176, v199, v97
	ds_bpermute_b32 v177, v199, v69
	ds_bpermute_b32 v178, v199, v101
	ds_bpermute_b32 v179, v199, v73
	ds_bpermute_b32 v180, v199, v105
	ds_bpermute_b32 v181, v199, v77
	ds_bpermute_b32 v182, v199, v109
	s_waitcnt lgkmcnt(0)
	v_cndmask_b32_e64 v216, v49, v167, s[40:41]
	v_cndmask_b32_e64 v217, v81, v168, s[40:41]
	v_cndmask_b32_e64 v218, v167, v49, s[40:41]
	v_cndmask_b32_e64 v219, v168, v81, s[40:41]
	v_fma_f32 v213, v12, v22, v216
	v_fma_f32 v214, v12, v23, v217
	v_fma_f32 v213, -v13, v23, v213
	v_fmac_f32_e32 v214, v13, v22
	v_fma_f32 v215, v12, v213, v218
	v_fma_f32 v248, v12, v214, v219
	v_fma_f32 v215, -v13, v214, v215
	v_fmac_f32_e32 v248, v13, v213
	v_cndmask_b32_e64 v183, v22, v213, s[40:41]
	v_cndmask_b32_e64 v184, v23, v214, s[40:41]
	v_cndmask_b32_e64 v224, v65, v175, s[40:41]
	v_cndmask_b32_e64 v225, v97, v176, s[40:41]
	v_cndmask_b32_e64 v226, v175, v65, s[40:41]
	v_cndmask_b32_e64 v227, v176, v97, s[40:41]
	v_fma_f32 v251, v20, v24, v224
	v_fma_f32 v252, v20, v25, v225
	v_fma_f32 v251, -v21, v25, v251
	v_fmac_f32_e32 v252, v21, v24
	v_fma_f32 v253, v20, v251, v226
	v_fma_f32 v211, v20, v252, v227
	v_fma_f32 v253, -v21, v252, v253
	v_fmac_f32_e32 v211, v21, v251
	v_cndmask_b32_e64 v191, v24, v251, s[40:41]
	v_cndmask_b32_e64 v192, v25, v252, s[40:41]
	v_cndmask_b32_e64 v216, v53, v169, s[40:41]
	v_cndmask_b32_e64 v217, v85, v170, s[40:41]
	v_cndmask_b32_e64 v218, v169, v53, s[40:41]
	v_cndmask_b32_e64 v219, v170, v85, s[40:41]
	v_fma_f32 v249, v12, v215, v216
	v_fma_f32 v250, v12, v248, v217
	v_fma_f32 v249, -v13, v248, v249
	v_fmac_f32_e32 v250, v13, v215
	v_fma_f32 v213, v12, v249, v218
	v_fma_f32 v214, v12, v250, v219
	v_fma_f32 v213, -v13, v250, v213
	v_fmac_f32_e32 v214, v13, v249
	v_cndmask_b32_e64 v185, v215, v249, s[40:41]
	v_cndmask_b32_e64 v186, v248, v250, s[40:41]
	v_cndmask_b32_e64 v224, v69, v177, s[40:41]
	v_cndmask_b32_e64 v225, v101, v178, s[40:41]
	v_cndmask_b32_e64 v226, v177, v69, s[40:41]
	v_cndmask_b32_e64 v227, v178, v101, s[40:41]
	v_fma_f32 v212, v20, v253, v224
	v_fma_f32 v209, v20, v211, v225
	v_fma_f32 v212, -v21, v211, v212
	v_fmac_f32_e32 v209, v21, v253
	v_fma_f32 v251, v20, v212, v226
	v_fma_f32 v252, v20, v209, v227
	v_fma_f32 v251, -v21, v209, v251
	v_fmac_f32_e32 v252, v21, v212
	v_cndmask_b32_e64 v193, v253, v212, s[40:41]
	v_cndmask_b32_e64 v194, v211, v209, s[40:41]
	v_cndmask_b32_e64 v216, v57, v171, s[40:41]
	v_cndmask_b32_e64 v217, v89, v172, s[40:41]
	v_cndmask_b32_e64 v218, v171, v57, s[40:41]
	v_cndmask_b32_e64 v219, v172, v89, s[40:41]
	v_fma_f32 v215, v12, v213, v216
	v_fma_f32 v248, v12, v214, v217
	v_fma_f32 v215, -v13, v214, v215
	v_fmac_f32_e32 v248, v13, v213
	v_fma_f32 v249, v12, v215, v218
	v_fma_f32 v250, v12, v248, v219
	v_fma_f32 v249, -v13, v248, v249
	v_fmac_f32_e32 v250, v13, v215
	v_cndmask_b32_e64 v187, v213, v215, s[40:41]
	v_cndmask_b32_e64 v188, v214, v248, s[40:41]
	v_cndmask_b32_e64 v224, v73, v179, s[40:41]
	v_cndmask_b32_e64 v225, v105, v180, s[40:41]
	v_cndmask_b32_e64 v226, v179, v73, s[40:41]
	v_cndmask_b32_e64 v227, v180, v105, s[40:41]
	v_fma_f32 v253, v20, v251, v224
	v_fma_f32 v211, v20, v252, v225
	v_fma_f32 v253, -v21, v252, v253
	v_fmac_f32_e32 v211, v21, v251
	v_fma_f32 v212, v20, v253, v226
	v_fma_f32 v209, v20, v211, v227
	v_fma_f32 v212, -v21, v211, v212
	v_fmac_f32_e32 v209, v21, v253
	v_cndmask_b32_e64 v195, v251, v253, s[40:41]
	v_cndmask_b32_e64 v196, v252, v211, s[40:41]
	v_cndmask_b32_e64 v216, v61, v173, s[40:41]
	v_cndmask_b32_e64 v217, v93, v174, s[40:41]
	v_cndmask_b32_e64 v218, v173, v61, s[40:41]
	v_cndmask_b32_e64 v219, v174, v93, s[40:41]
	v_fma_f32 v213, v12, v249, v216
	v_fma_f32 v214, v12, v250, v217
	v_fma_f32 v213, -v13, v250, v213
	v_fmac_f32_e32 v214, v13, v249
	v_fma_f32 v215, v12, v213, v218
	v_fma_f32 v248, v12, v214, v219
	v_fma_f32 v215, -v13, v214, v215
	v_fmac_f32_e32 v248, v13, v213
	v_cndmask_b32_e64 v189, v249, v213, s[40:41]
	v_cndmask_b32_e64 v190, v250, v214, s[40:41]
	v_cndmask_b32_e64 v224, v77, v181, s[40:41]
	v_cndmask_b32_e64 v225, v109, v182, s[40:41]
	v_cndmask_b32_e64 v226, v181, v77, s[40:41]
	v_cndmask_b32_e64 v227, v182, v109, s[40:41]
	v_fma_f32 v251, v20, v212, v224
	v_fma_f32 v252, v20, v209, v225
	v_fma_f32 v251, -v21, v209, v251
	v_fmac_f32_e32 v252, v21, v212
	v_fma_f32 v253, v20, v251, v226
	v_fma_f32 v211, v20, v252, v227
	v_fma_f32 v253, -v21, v252, v253
	v_fmac_f32_e32 v211, v21, v251
	v_cndmask_b32_e64 v197, v212, v251, s[40:41]
	v_cndmask_b32_e64 v198, v209, v252, s[40:41]
	v_mov_b32_e32 v22, v215
	v_mov_b32_e32 v23, v248
	v_mov_b32_e32 v24, v253
	v_mov_b32_e32 v25, v211
	v_fmac_f32_e32 v46, v6, v183
	v_fmac_f32_e32 v78, v6, v184
	v_fma_f32 v46, -v7, v184, v46
	v_fmac_f32_e32 v78, v7, v183
	v_fmac_f32_e32 v47, v8, v183
	v_fmac_f32_e32 v79, v8, v184
	v_fma_f32 v47, -v9, v184, v47
	v_fmac_f32_e32 v79, v9, v183
	v_fmac_f32_e32 v48, v10, v183
	v_fmac_f32_e32 v80, v10, v184
	v_fma_f32 v48, -v11, v184, v48
	v_fmac_f32_e32 v80, v11, v183
	v_fmac_f32_e32 v49, v12, v183
	v_fmac_f32_e32 v81, v12, v184
	v_fma_f32 v49, -v13, v184, v49
	v_fmac_f32_e32 v81, v13, v183
	v_fmac_f32_e32 v50, v6, v185
	v_fmac_f32_e32 v82, v6, v186
	v_fma_f32 v50, -v7, v186, v50
	v_fmac_f32_e32 v82, v7, v185
	v_fmac_f32_e32 v51, v8, v185
	v_fmac_f32_e32 v83, v8, v186
	v_fma_f32 v51, -v9, v186, v51
	v_fmac_f32_e32 v83, v9, v185
	v_fmac_f32_e32 v52, v10, v185
	v_fmac_f32_e32 v84, v10, v186
	v_fma_f32 v52, -v11, v186, v52
	v_fmac_f32_e32 v84, v11, v185
	v_fmac_f32_e32 v53, v12, v185
	v_fmac_f32_e32 v85, v12, v186
	v_fma_f32 v53, -v13, v186, v53
	v_fmac_f32_e32 v85, v13, v185
	v_fmac_f32_e32 v54, v6, v187
	v_fmac_f32_e32 v86, v6, v188
	v_fma_f32 v54, -v7, v188, v54
	v_fmac_f32_e32 v86, v7, v187
	v_fmac_f32_e32 v55, v8, v187
	v_fmac_f32_e32 v87, v8, v188
	v_fma_f32 v55, -v9, v188, v55
	v_fmac_f32_e32 v87, v9, v187
	v_fmac_f32_e32 v56, v10, v187
	v_fmac_f32_e32 v88, v10, v188
	v_fma_f32 v56, -v11, v188, v56
	v_fmac_f32_e32 v88, v11, v187
	v_fmac_f32_e32 v57, v12, v187
	v_fmac_f32_e32 v89, v12, v188
	v_fma_f32 v57, -v13, v188, v57
	v_fmac_f32_e32 v89, v13, v187
	v_fmac_f32_e32 v58, v6, v189
	v_fmac_f32_e32 v90, v6, v190
	v_fma_f32 v58, -v7, v190, v58
	v_fmac_f32_e32 v90, v7, v189
	v_fmac_f32_e32 v59, v8, v189
	v_fmac_f32_e32 v91, v8, v190
	v_fma_f32 v59, -v9, v190, v59
	v_fmac_f32_e32 v91, v9, v189
	v_fmac_f32_e32 v60, v10, v189
	v_fmac_f32_e32 v92, v10, v190
	v_fma_f32 v60, -v11, v190, v60
	v_fmac_f32_e32 v92, v11, v189
	v_fmac_f32_e32 v61, v12, v189
	v_fmac_f32_e32 v93, v12, v190
	v_fma_f32 v61, -v13, v190, v61
	v_fmac_f32_e32 v93, v13, v189
	v_fmac_f32_e32 v62, v14, v191
	v_fmac_f32_e32 v94, v14, v192
	v_fma_f32 v62, -v15, v192, v62
	v_fmac_f32_e32 v94, v15, v191
	v_fmac_f32_e32 v63, v16, v191
	v_fmac_f32_e32 v95, v16, v192
	v_fma_f32 v63, -v17, v192, v63
	v_fmac_f32_e32 v95, v17, v191
	v_fmac_f32_e32 v64, v18, v191
	v_fmac_f32_e32 v96, v18, v192
	v_fma_f32 v64, -v19, v192, v64
	v_fmac_f32_e32 v96, v19, v191
	v_fmac_f32_e32 v65, v20, v191
	v_fmac_f32_e32 v97, v20, v192
	v_fma_f32 v65, -v21, v192, v65
	v_fmac_f32_e32 v97, v21, v191
	v_fmac_f32_e32 v66, v14, v193
	v_fmac_f32_e32 v98, v14, v194
	v_fma_f32 v66, -v15, v194, v66
	v_fmac_f32_e32 v98, v15, v193
	v_fmac_f32_e32 v67, v16, v193
	v_fmac_f32_e32 v99, v16, v194
	v_fma_f32 v67, -v17, v194, v67
	v_fmac_f32_e32 v99, v17, v193
	v_fmac_f32_e32 v68, v18, v193
	v_fmac_f32_e32 v100, v18, v194
	v_fma_f32 v68, -v19, v194, v68
	v_fmac_f32_e32 v100, v19, v193
	v_fmac_f32_e32 v69, v20, v193
	v_fmac_f32_e32 v101, v20, v194
	v_fma_f32 v69, -v21, v194, v69
	v_fmac_f32_e32 v101, v21, v193
	v_fmac_f32_e32 v70, v14, v195
	v_fmac_f32_e32 v102, v14, v196
	v_fma_f32 v70, -v15, v196, v70
	v_fmac_f32_e32 v102, v15, v195
	v_fmac_f32_e32 v71, v16, v195
	v_fmac_f32_e32 v103, v16, v196
	v_fma_f32 v71, -v17, v196, v71
	v_fmac_f32_e32 v103, v17, v195
	v_fmac_f32_e32 v72, v18, v195
	v_fmac_f32_e32 v104, v18, v196
	v_fma_f32 v72, -v19, v196, v72
	v_fmac_f32_e32 v104, v19, v195
	v_fmac_f32_e32 v73, v20, v195
	v_fmac_f32_e32 v105, v20, v196
	v_fma_f32 v73, -v21, v196, v73
	v_fmac_f32_e32 v105, v21, v195
	v_fmac_f32_e32 v74, v14, v197
	v_fmac_f32_e32 v106, v14, v198
	v_fma_f32 v74, -v15, v198, v74
	v_fmac_f32_e32 v106, v15, v197
	v_fmac_f32_e32 v75, v16, v197
	v_fmac_f32_e32 v107, v16, v198
	v_fma_f32 v75, -v17, v198, v75
	v_fmac_f32_e32 v107, v17, v197
	v_fmac_f32_e32 v76, v18, v197
	v_fmac_f32_e32 v108, v18, v198
	v_fma_f32 v76, -v19, v198, v76
	v_fmac_f32_e32 v108, v19, v197
	v_fmac_f32_e32 v77, v20, v197
	v_fmac_f32_e32 v109, v20, v198
	v_fma_f32 v77, -v21, v198, v77
	v_fmac_f32_e32 v109, v21, v197
	v_cvt_pk_bf16_f32 v216, v46, v47
	v_cvt_pk_bf16_f32 v217, v48, v49
	ds_write_b64 v200, v[216:217] offset:0
	v_cvt_pk_bf16_f32 v218, v50, v51
	v_cvt_pk_bf16_f32 v219, v52, v53
	ds_write_b64 v200, v[218:219] offset:16
	v_cvt_pk_bf16_f32 v220, v54, v55
	v_cvt_pk_bf16_f32 v221, v56, v57
	ds_write_b64 v200, v[220:221] offset:32
	v_cvt_pk_bf16_f32 v222, v58, v59
	v_cvt_pk_bf16_f32 v223, v60, v61
	ds_write_b64 v200, v[222:223] offset:48
	v_cvt_pk_bf16_f32 v224, v62, v63
	v_cvt_pk_bf16_f32 v225, v64, v65
	ds_write_b64 v200, v[224:225] offset:2304
	v_cvt_pk_bf16_f32 v226, v66, v67
	v_cvt_pk_bf16_f32 v227, v68, v69
	ds_write_b64 v200, v[226:227] offset:2320
	v_cvt_pk_bf16_f32 v228, v70, v71
	v_cvt_pk_bf16_f32 v229, v72, v73
	ds_write_b64 v200, v[228:229] offset:2336
	v_cvt_pk_bf16_f32 v230, v74, v75
	v_cvt_pk_bf16_f32 v231, v76, v77
	ds_write_b64 v200, v[230:231] offset:2352
	v_cvt_pk_bf16_f32 v232, v78, v79
	v_cvt_pk_bf16_f32 v233, v80, v81
	ds_write_b64 v200, v[232:233] offset:4608
	v_cvt_pk_bf16_f32 v234, v82, v83
	v_cvt_pk_bf16_f32 v235, v84, v85
	ds_write_b64 v200, v[234:235] offset:4624
	v_cvt_pk_bf16_f32 v236, v86, v87
	v_cvt_pk_bf16_f32 v237, v88, v89
	ds_write_b64 v200, v[236:237] offset:4640
	v_cvt_pk_bf16_f32 v238, v90, v91
	v_cvt_pk_bf16_f32 v239, v92, v93
	ds_write_b64 v200, v[238:239] offset:4656
	v_cvt_pk_bf16_f32 v240, v94, v95
	v_cvt_pk_bf16_f32 v241, v96, v97
	ds_write_b64 v200, v[240:241] offset:6912
	v_cvt_pk_bf16_f32 v242, v98, v99
	v_cvt_pk_bf16_f32 v243, v100, v101
	ds_write_b64 v200, v[242:243] offset:6928
	v_cvt_pk_bf16_f32 v244, v102, v103
	v_cvt_pk_bf16_f32 v245, v104, v105
	ds_write_b64 v200, v[244:245] offset:6944
	v_cvt_pk_bf16_f32 v246, v106, v107
	v_cvt_pk_bf16_f32 v247, v108, v109
	ds_write_b64 v200, v[246:247] offset:6960
	s_waitcnt lgkmcnt(0)
	ds_read_b64_tr_b16 v[216:217], v201 offset:0
	ds_read_b64_tr_b16 v[218:219], v201 offset:288
	ds_read_b64_tr_b16 v[220:221], v201 offset:1152
	ds_read_b64_tr_b16 v[222:223], v201 offset:1440
	ds_read_b64_tr_b16 v[224:225], v201 offset:2304
	ds_read_b64_tr_b16 v[226:227], v201 offset:2592
	ds_read_b64_tr_b16 v[228:229], v201 offset:3456
	ds_read_b64_tr_b16 v[230:231], v201 offset:3744
	ds_read_b64_tr_b16 v[232:233], v201 offset:4608
	ds_read_b64_tr_b16 v[234:235], v201 offset:4896
	ds_read_b64_tr_b16 v[236:237], v201 offset:5760
	ds_read_b64_tr_b16 v[238:239], v201 offset:6048
	ds_read_b64_tr_b16 v[240:241], v201 offset:6912
	ds_read_b64_tr_b16 v[242:243], v201 offset:7200
	ds_read_b64_tr_b16 v[244:245], v201 offset:8064
	ds_read_b64_tr_b16 v[246:247], v201 offset:8352
	s_waitcnt lgkmcnt(14)
	v_mfma_f32_32x32x16_bf16 v[110:125], v[216:219], v[134:137], v[110:125]
	s_waitcnt lgkmcnt(12)
	v_mfma_f32_32x32x16_bf16 v[110:125], v[220:223], v[138:141], v[110:125]
	s_waitcnt lgkmcnt(10)
	v_mfma_f32_32x32x16_bf16 v[110:125], v[224:227], v[142:145], v[110:125]
	s_waitcnt lgkmcnt(8)
	v_mfma_f32_32x32x16_bf16 v[110:125], v[228:231], v[146:149], v[110:125]
	s_waitcnt lgkmcnt(6)
	v_mfma_f32_32x32x16_bf16 v[110:125], v[232:235], v[150:153], v[110:125]
	s_waitcnt lgkmcnt(4)
	v_mfma_f32_32x32x16_bf16 v[110:125], v[236:239], v[154:157], v[110:125]
	s_waitcnt lgkmcnt(2)
	v_mfma_f32_32x32x16_bf16 v[110:125], v[240:243], v[158:161], v[110:125]
	s_waitcnt lgkmcnt(0)
	v_mfma_f32_32x32x16_bf16 v[110:125], v[244:247], v[162:165], v[110:125]
	s_nop 7
	s_nop 3
	s_mov_b64 exec, s[44:45]
	ds_write_b32 v202, v110 offset:0
	ds_write_b32 v202, v111 offset:64
	ds_write_b32 v202, v112 offset:128
	ds_write_b32 v202, v113 offset:192
	ds_write_b32 v202, v114 offset:512
	ds_write_b32 v202, v115 offset:576
	ds_write_b32 v202, v116 offset:640
	ds_write_b32 v202, v117 offset:704
	ds_write_b32 v202, v118 offset:1024
	ds_write_b32 v202, v119 offset:1088
	ds_write_b32 v202, v120 offset:1152
	ds_write_b32 v202, v121 offset:1216
	ds_write_b32 v202, v122 offset:1536
	ds_write_b32 v202, v123 offset:1600
	ds_write_b32 v202, v124 offset:1664
	ds_write_b32 v202, v125 offset:1728
	s_mov_b64 exec, -1
	s_waitcnt lgkmcnt(0)
	ds_read_b128 v[216:219], v203
	ds_read_b128 v[220:223], v203 offset:16
	s_waitcnt lgkmcnt(0)
	v_mul_f32_e32 v224, 0x3d372713, v216
	v_mul_f32_e32 v225, 0x3d372713, v217
	v_mul_f32_e32 v226, 0x3d372713, v218
	v_mul_f32_e32 v227, 0x3d372713, v219
	v_mul_f32_e32 v228, 0x3d372713, v220
	v_mul_f32_e32 v229, 0x3d372713, v221
	v_mul_f32_e32 v230, 0x3d372713, v222
	v_mul_f32_e32 v231, 0x3d372713, v223
	v_mul_f32_e32 v224, v216, v224
	v_mul_f32_e32 v225, v217, v225
	v_mul_f32_e32 v226, v218, v226
	v_mul_f32_e32 v227, v219, v227
	v_mul_f32_e32 v228, v220, v228
	v_mul_f32_e32 v229, v221, v229
	v_mul_f32_e32 v230, v222, v230
	v_mul_f32_e32 v231, v223, v231
	v_fma_f32 v224, v216, v224, v216
	v_fma_f32 v225, v217, v225, v217
	v_fma_f32 v226, v218, v226, v218
	v_fma_f32 v227, v219, v227, v219
	v_fma_f32 v228, v220, v228, v220
	v_fma_f32 v229, v221, v229, v221
	v_fma_f32 v230, v222, v230, v222
	v_fma_f32 v231, v223, v231, v223
	v_mul_f32_e32 v224, 0x3f4c422a, v224
	v_mul_f32_e32 v225, 0x3f4c422a, v225
	v_mul_f32_e32 v226, 0x3f4c422a, v226
	v_mul_f32_e32 v227, 0x3f4c422a, v227
	v_mul_f32_e32 v228, 0x3f4c422a, v228
	v_mul_f32_e32 v229, 0x3f4c422a, v229
	v_mul_f32_e32 v230, 0x3f4c422a, v230
	v_mul_f32_e32 v231, 0x3f4c422a, v231
	v_add_f32_e32 v224, v224, v224
	v_add_f32_e32 v225, v225, v225
	v_add_f32_e32 v226, v226, v226
	v_add_f32_e32 v227, v227, v227
	v_add_f32_e32 v228, v228, v228
	v_add_f32_e32 v229, v229, v229
	v_add_f32_e32 v230, v230, v230
	v_add_f32_e32 v231, v231, v231
	v_mul_f32_e32 v224, 0xbfb8aa3b, v224
	v_mul_f32_e32 v225, 0xbfb8aa3b, v225
	v_mul_f32_e32 v226, 0xbfb8aa3b, v226
	v_mul_f32_e32 v227, 0xbfb8aa3b, v227
	v_mul_f32_e32 v228, 0xbfb8aa3b, v228
	v_mul_f32_e32 v229, 0xbfb8aa3b, v229
	v_mul_f32_e32 v230, 0xbfb8aa3b, v230
	v_mul_f32_e32 v231, 0xbfb8aa3b, v231
	v_exp_f32_e32 v224, v224
	v_exp_f32_e32 v225, v225
	v_exp_f32_e32 v226, v226
	v_exp_f32_e32 v227, v227
	v_exp_f32_e32 v228, v228
	v_exp_f32_e32 v229, v229
	v_exp_f32_e32 v230, v230
	v_exp_f32_e32 v231, v231
	s_nop 0
	v_add_f32_e32 v224, 1.0, v224
	v_add_f32_e32 v225, 1.0, v225
	v_add_f32_e32 v226, 1.0, v226
	v_add_f32_e32 v227, 1.0, v227
	v_add_f32_e32 v228, 1.0, v228
	v_add_f32_e32 v229, 1.0, v229
	v_add_f32_e32 v230, 1.0, v230
	v_add_f32_e32 v231, 1.0, v231
	v_rcp_f32_e32 v224, v224
	v_rcp_f32_e32 v225, v225
	v_rcp_f32_e32 v226, v226
	v_rcp_f32_e32 v227, v227
	v_rcp_f32_e32 v228, v228
	v_rcp_f32_e32 v229, v229
	v_rcp_f32_e32 v230, v230
	v_rcp_f32_e32 v231, v231
	s_nop 0
	v_mul_f32_e32 v224, v216, v224
	v_mul_f32_e32 v225, v217, v225
	v_mul_f32_e32 v226, v218, v226
	v_mul_f32_e32 v227, v219, v227
	v_mul_f32_e32 v228, v220, v228
	v_mul_f32_e32 v229, v221, v229
	v_mul_f32_e32 v230, v222, v230
	v_mul_f32_e32 v231, v223, v231
	v_cvt_pk_bf16_f32 v232, v224, v225
	v_cvt_pk_bf16_f32 v233, v226, v227
	v_cvt_pk_bf16_f32 v234, v228, v229
	v_cvt_pk_bf16_f32 v235, v230, v231
	s_add_u32 s70, s60, 0x0
	s_addc_u32 s71, s61, 0
	global_store_dwordx4 v205, v[232:235], s[70:71]
	s_waitcnt vmcnt(1)
	v_mfma_f32_32x32x16_bf16 v[46:61], v[130:133], v[26:29], 0
	v_mfma_f32_32x32x16_bf16 v[78:93], v[130:133], v[34:37], 0
	v_mfma_f32_32x32x16_bf16 v[62:77], v[130:133], v[30:33], 0
	v_mfma_f32_32x32x16_bf16 v[94:109], v[130:133], v[38:41], 0
	v_mfma_f32_32x32x16_bf16 v[110:125], v[130:133], v[42:45], 0
	s_add_u32 s70, s58, 0x40000
	s_addc_u32 s71, s59, 0
	global_load_dwordx4 v[126:129], v204, s[70:71]
	s_nop 7
	s_nop 1
	v_fmac_f32_e32 v47, v6, v46
	v_fmac_f32_e32 v79, v6, v78
	v_fma_f32 v47, -v7, v78, v47
	v_fmac_f32_e32 v79, v7, v46
	v_fmac_f32_e32 v51, v6, v50
	v_fmac_f32_e32 v83, v6, v82
	v_fma_f32 v51, -v7, v82, v51
	v_fmac_f32_e32 v83, v7, v50
	v_fmac_f32_e32 v55, v6, v54
	v_fmac_f32_e32 v87, v6, v86
	v_fma_f32 v55, -v7, v86, v55
	v_fmac_f32_e32 v87, v7, v54
	v_fmac_f32_e32 v59, v6, v58
	v_fmac_f32_e32 v91, v6, v90
	v_fma_f32 v59, -v7, v90, v59
	v_fmac_f32_e32 v91, v7, v58
	v_fmac_f32_e32 v63, v14, v62
	v_fmac_f32_e32 v95, v14, v94
	v_fma_f32 v63, -v15, v94, v63
	v_fmac_f32_e32 v95, v15, v62
	v_fmac_f32_e32 v67, v14, v66
	v_fmac_f32_e32 v99, v14, v98
	v_fma_f32 v67, -v15, v98, v67
	v_fmac_f32_e32 v99, v15, v66
	v_fmac_f32_e32 v71, v14, v70
	v_fmac_f32_e32 v103, v14, v102
	v_fma_f32 v71, -v15, v102, v71
	v_fmac_f32_e32 v103, v15, v70
	v_fmac_f32_e32 v75, v14, v74
	v_fmac_f32_e32 v107, v14, v106
	v_fma_f32 v75, -v15, v106, v75
	v_fmac_f32_e32 v107, v15, v74
	v_fmac_f32_e32 v48, v6, v47
	v_fmac_f32_e32 v80, v6, v79
	v_fma_f32 v48, -v7, v79, v48
	v_fmac_f32_e32 v80, v7, v47
	v_fmac_f32_e32 v52, v6, v51
	v_fmac_f32_e32 v84, v6, v83
	v_fma_f32 v52, -v7, v83, v52
	v_fmac_f32_e32 v84, v7, v51
	v_fmac_f32_e32 v56, v6, v55
	v_fmac_f32_e32 v88, v6, v87
	v_fma_f32 v56, -v7, v87, v56
	v_fmac_f32_e32 v88, v7, v55
	v_fmac_f32_e32 v60, v6, v59
	v_fmac_f32_e32 v92, v6, v91
	v_fma_f32 v60, -v7, v91, v60
	v_fmac_f32_e32 v92, v7, v59
	v_fmac_f32_e32 v64, v14, v63
	v_fmac_f32_e32 v96, v14, v95
	v_fma_f32 v64, -v15, v95, v64
	v_fmac_f32_e32 v96, v15, v63
	v_fmac_f32_e32 v68, v14, v67
	v_fmac_f32_e32 v100, v14, v99
	v_fma_f32 v68, -v15, v99, v68
	v_fmac_f32_e32 v100, v15, v67
	v_fmac_f32_e32 v72, v14, v71
	v_fmac_f32_e32 v104, v14, v103
	v_fma_f32 v72, -v15, v103, v72
	v_fmac_f32_e32 v104, v15, v71
	v_fmac_f32_e32 v76, v14, v75
	v_fmac_f32_e32 v108, v14, v107
	v_fma_f32 v76, -v15, v107, v76
	v_fmac_f32_e32 v108, v15, v75
	v_fmac_f32_e32 v49, v6, v48
	v_fmac_f32_e32 v81, v6, v80
	v_fma_f32 v49, -v7, v80, v49
	v_fmac_f32_e32 v81, v7, v48
	v_fmac_f32_e32 v53, v6, v52
	v_fmac_f32_e32 v85, v6, v84
	v_fma_f32 v53, -v7, v84, v53
	v_fmac_f32_e32 v85, v7, v52
	v_fmac_f32_e32 v57, v6, v56
	v_fmac_f32_e32 v89, v6, v88
	v_fma_f32 v57, -v7, v88, v57
	v_fmac_f32_e32 v89, v7, v56
	v_fmac_f32_e32 v61, v6, v60
	v_fmac_f32_e32 v93, v6, v92
	v_fma_f32 v61, -v7, v92, v61
	v_fmac_f32_e32 v93, v7, v60
	v_fmac_f32_e32 v65, v14, v64
	v_fmac_f32_e32 v97, v14, v96
	v_fma_f32 v65, -v15, v96, v65
	v_fmac_f32_e32 v97, v15, v64
	v_fmac_f32_e32 v69, v14, v68
	v_fmac_f32_e32 v101, v14, v100
	v_fma_f32 v69, -v15, v100, v69
	v_fmac_f32_e32 v101, v15, v68
	v_fmac_f32_e32 v73, v14, v72
	v_fmac_f32_e32 v105, v14, v104
	v_fma_f32 v73, -v15, v104, v73
	v_fmac_f32_e32 v105, v15, v72
	v_fmac_f32_e32 v77, v14, v76
	v_fmac_f32_e32 v109, v14, v108
	v_fma_f32 v77, -v15, v108, v77
	v_fmac_f32_e32 v109, v15, v76
	ds_bpermute_b32 v167, v199, v49
	ds_bpermute_b32 v168, v199, v81
	ds_bpermute_b32 v169, v199, v53
	ds_bpermute_b32 v170, v199, v85
	ds_bpermute_b32 v171, v199, v57
	ds_bpermute_b32 v172, v199, v89
	ds_bpermute_b32 v173, v199, v61
	ds_bpermute_b32 v174, v199, v93
	ds_bpermute_b32 v175, v199, v65
	ds_bpermute_b32 v176, v199, v97
	ds_bpermute_b32 v177, v199, v69
	ds_bpermute_b32 v178, v199, v101
	ds_bpermute_b32 v179, v199, v73
	ds_bpermute_b32 v180, v199, v105
	ds_bpermute_b32 v181, v199, v77
	ds_bpermute_b32 v182, v199, v109
	s_waitcnt lgkmcnt(0)
	v_cndmask_b32_e64 v216, v49, v167, s[40:41]
	v_cndmask_b32_e64 v217, v81, v168, s[40:41]
	v_cndmask_b32_e64 v218, v167, v49, s[40:41]
	v_cndmask_b32_e64 v219, v168, v81, s[40:41]
	v_fma_f32 v213, v12, v22, v216
	v_fma_f32 v214, v12, v23, v217
	v_fma_f32 v213, -v13, v23, v213
	v_fmac_f32_e32 v214, v13, v22
	v_fma_f32 v215, v12, v213, v218
	v_fma_f32 v248, v12, v214, v219
	v_fma_f32 v215, -v13, v214, v215
	v_fmac_f32_e32 v248, v13, v213
	v_cndmask_b32_e64 v183, v22, v213, s[40:41]
	v_cndmask_b32_e64 v184, v23, v214, s[40:41]
	v_cndmask_b32_e64 v224, v65, v175, s[40:41]
	v_cndmask_b32_e64 v225, v97, v176, s[40:41]
	v_cndmask_b32_e64 v226, v175, v65, s[40:41]
	v_cndmask_b32_e64 v227, v176, v97, s[40:41]
	v_fma_f32 v251, v20, v24, v224
	v_fma_f32 v252, v20, v25, v225
	v_fma_f32 v251, -v21, v25, v251
	v_fmac_f32_e32 v252, v21, v24
	v_fma_f32 v253, v20, v251, v226
	v_fma_f32 v211, v20, v252, v227
	v_fma_f32 v253, -v21, v252, v253
	v_fmac_f32_e32 v211, v21, v251
	v_cndmask_b32_e64 v191, v24, v251, s[40:41]
	v_cndmask_b32_e64 v192, v25, v252, s[40:41]
	v_cndmask_b32_e64 v216, v53, v169, s[40:41]
	v_cndmask_b32_e64 v217, v85, v170, s[40:41]
	v_cndmask_b32_e64 v218, v169, v53, s[40:41]
	v_cndmask_b32_e64 v219, v170, v85, s[40:41]
	v_fma_f32 v249, v12, v215, v216
	v_fma_f32 v250, v12, v248, v217
	v_fma_f32 v249, -v13, v248, v249
	v_fmac_f32_e32 v250, v13, v215
	v_fma_f32 v213, v12, v249, v218
	v_fma_f32 v214, v12, v250, v219
	v_fma_f32 v213, -v13, v250, v213
	v_fmac_f32_e32 v214, v13, v249
	v_cndmask_b32_e64 v185, v215, v249, s[40:41]
	v_cndmask_b32_e64 v186, v248, v250, s[40:41]
	v_cndmask_b32_e64 v224, v69, v177, s[40:41]
	v_cndmask_b32_e64 v225, v101, v178, s[40:41]
	v_cndmask_b32_e64 v226, v177, v69, s[40:41]
	v_cndmask_b32_e64 v227, v178, v101, s[40:41]
	v_fma_f32 v212, v20, v253, v224
	v_fma_f32 v209, v20, v211, v225
	v_fma_f32 v212, -v21, v211, v212
	v_fmac_f32_e32 v209, v21, v253
	v_fma_f32 v251, v20, v212, v226
	v_fma_f32 v252, v20, v209, v227
	v_fma_f32 v251, -v21, v209, v251
	v_fmac_f32_e32 v252, v21, v212
	v_cndmask_b32_e64 v193, v253, v212, s[40:41]
	v_cndmask_b32_e64 v194, v211, v209, s[40:41]
	v_cndmask_b32_e64 v216, v57, v171, s[40:41]
	v_cndmask_b32_e64 v217, v89, v172, s[40:41]
	v_cndmask_b32_e64 v218, v171, v57, s[40:41]
	v_cndmask_b32_e64 v219, v172, v89, s[40:41]
	v_fma_f32 v215, v12, v213, v216
	v_fma_f32 v248, v12, v214, v217
	v_fma_f32 v215, -v13, v214, v215
	v_fmac_f32_e32 v248, v13, v213
	v_fma_f32 v249, v12, v215, v218
	v_fma_f32 v250, v12, v248, v219
	v_fma_f32 v249, -v13, v248, v249
	v_fmac_f32_e32 v250, v13, v215
	v_cndmask_b32_e64 v187, v213, v215, s[40:41]
	v_cndmask_b32_e64 v188, v214, v248, s[40:41]
	v_cndmask_b32_e64 v224, v73, v179, s[40:41]
	v_cndmask_b32_e64 v225, v105, v180, s[40:41]
	v_cndmask_b32_e64 v226, v179, v73, s[40:41]
	v_cndmask_b32_e64 v227, v180, v105, s[40:41]
	v_fma_f32 v253, v20, v251, v224
	v_fma_f32 v211, v20, v252, v225
	v_fma_f32 v253, -v21, v252, v253
	v_fmac_f32_e32 v211, v21, v251
	v_fma_f32 v212, v20, v253, v226
	v_fma_f32 v209, v20, v211, v227
	v_fma_f32 v212, -v21, v211, v212
	v_fmac_f32_e32 v209, v21, v253
	v_cndmask_b32_e64 v195, v251, v253, s[40:41]
	v_cndmask_b32_e64 v196, v252, v211, s[40:41]
	v_cndmask_b32_e64 v216, v61, v173, s[40:41]
	v_cndmask_b32_e64 v217, v93, v174, s[40:41]
	v_cndmask_b32_e64 v218, v173, v61, s[40:41]
	v_cndmask_b32_e64 v219, v174, v93, s[40:41]
	v_fma_f32 v213, v12, v249, v216
	v_fma_f32 v214, v12, v250, v217
	v_fma_f32 v213, -v13, v250, v213
	v_fmac_f32_e32 v214, v13, v249
	v_fma_f32 v215, v12, v213, v218
	v_fma_f32 v248, v12, v214, v219
	v_fma_f32 v215, -v13, v214, v215
	v_fmac_f32_e32 v248, v13, v213
	v_cndmask_b32_e64 v189, v249, v213, s[40:41]
	v_cndmask_b32_e64 v190, v250, v214, s[40:41]
	v_cndmask_b32_e64 v224, v77, v181, s[40:41]
	v_cndmask_b32_e64 v225, v109, v182, s[40:41]
	v_cndmask_b32_e64 v226, v181, v77, s[40:41]
	v_cndmask_b32_e64 v227, v182, v109, s[40:41]
	v_fma_f32 v251, v20, v212, v224
	v_fma_f32 v252, v20, v209, v225
	v_fma_f32 v251, -v21, v209, v251
	v_fmac_f32_e32 v252, v21, v212
	v_fma_f32 v253, v20, v251, v226
	v_fma_f32 v211, v20, v252, v227
	v_fma_f32 v253, -v21, v252, v253
	v_fmac_f32_e32 v211, v21, v251
	v_cndmask_b32_e64 v197, v212, v251, s[40:41]
	v_cndmask_b32_e64 v198, v209, v252, s[40:41]
	v_mov_b32_e32 v22, v215
	v_mov_b32_e32 v23, v248
	v_mov_b32_e32 v24, v253
	v_mov_b32_e32 v25, v211
	v_fmac_f32_e32 v46, v6, v183
	v_fmac_f32_e32 v78, v6, v184
	v_fma_f32 v46, -v7, v184, v46
	v_fmac_f32_e32 v78, v7, v183
	v_fmac_f32_e32 v47, v8, v183
	v_fmac_f32_e32 v79, v8, v184
	v_fma_f32 v47, -v9, v184, v47
	v_fmac_f32_e32 v79, v9, v183
	v_fmac_f32_e32 v48, v10, v183
	v_fmac_f32_e32 v80, v10, v184
	v_fma_f32 v48, -v11, v184, v48
	v_fmac_f32_e32 v80, v11, v183
	v_fmac_f32_e32 v49, v12, v183
	v_fmac_f32_e32 v81, v12, v184
	v_fma_f32 v49, -v13, v184, v49
	v_fmac_f32_e32 v81, v13, v183
	v_fmac_f32_e32 v50, v6, v185
	v_fmac_f32_e32 v82, v6, v186
	v_fma_f32 v50, -v7, v186, v50
	v_fmac_f32_e32 v82, v7, v185
	v_fmac_f32_e32 v51, v8, v185
	v_fmac_f32_e32 v83, v8, v186
	v_fma_f32 v51, -v9, v186, v51
	v_fmac_f32_e32 v83, v9, v185
	v_fmac_f32_e32 v52, v10, v185
	v_fmac_f32_e32 v84, v10, v186
	v_fma_f32 v52, -v11, v186, v52
	v_fmac_f32_e32 v84, v11, v185
	v_fmac_f32_e32 v53, v12, v185
	v_fmac_f32_e32 v85, v12, v186
	v_fma_f32 v53, -v13, v186, v53
	v_fmac_f32_e32 v85, v13, v185
	v_fmac_f32_e32 v54, v6, v187
	v_fmac_f32_e32 v86, v6, v188
	v_fma_f32 v54, -v7, v188, v54
	v_fmac_f32_e32 v86, v7, v187
	v_fmac_f32_e32 v55, v8, v187
	v_fmac_f32_e32 v87, v8, v188
	v_fma_f32 v55, -v9, v188, v55
	v_fmac_f32_e32 v87, v9, v187
	v_fmac_f32_e32 v56, v10, v187
	v_fmac_f32_e32 v88, v10, v188
	v_fma_f32 v56, -v11, v188, v56
	v_fmac_f32_e32 v88, v11, v187
	v_fmac_f32_e32 v57, v12, v187
	v_fmac_f32_e32 v89, v12, v188
	v_fma_f32 v57, -v13, v188, v57
	v_fmac_f32_e32 v89, v13, v187
	v_fmac_f32_e32 v58, v6, v189
	v_fmac_f32_e32 v90, v6, v190
	v_fma_f32 v58, -v7, v190, v58
	v_fmac_f32_e32 v90, v7, v189
	v_fmac_f32_e32 v59, v8, v189
	v_fmac_f32_e32 v91, v8, v190
	v_fma_f32 v59, -v9, v190, v59
	v_fmac_f32_e32 v91, v9, v189
	v_fmac_f32_e32 v60, v10, v189
	v_fmac_f32_e32 v92, v10, v190
	v_fma_f32 v60, -v11, v190, v60
	v_fmac_f32_e32 v92, v11, v189
	v_fmac_f32_e32 v61, v12, v189
	v_fmac_f32_e32 v93, v12, v190
	v_fma_f32 v61, -v13, v190, v61
	v_fmac_f32_e32 v93, v13, v189
	v_fmac_f32_e32 v62, v14, v191
	v_fmac_f32_e32 v94, v14, v192
	v_fma_f32 v62, -v15, v192, v62
	v_fmac_f32_e32 v94, v15, v191
	v_fmac_f32_e32 v63, v16, v191
	v_fmac_f32_e32 v95, v16, v192
	v_fma_f32 v63, -v17, v192, v63
	v_fmac_f32_e32 v95, v17, v191
	v_fmac_f32_e32 v64, v18, v191
	v_fmac_f32_e32 v96, v18, v192
	v_fma_f32 v64, -v19, v192, v64
	v_fmac_f32_e32 v96, v19, v191
	v_fmac_f32_e32 v65, v20, v191
	v_fmac_f32_e32 v97, v20, v192
	v_fma_f32 v65, -v21, v192, v65
	v_fmac_f32_e32 v97, v21, v191
	v_fmac_f32_e32 v66, v14, v193
	v_fmac_f32_e32 v98, v14, v194
	v_fma_f32 v66, -v15, v194, v66
	v_fmac_f32_e32 v98, v15, v193
	v_fmac_f32_e32 v67, v16, v193
	v_fmac_f32_e32 v99, v16, v194
	v_fma_f32 v67, -v17, v194, v67
	v_fmac_f32_e32 v99, v17, v193
	v_fmac_f32_e32 v68, v18, v193
	v_fmac_f32_e32 v100, v18, v194
	v_fma_f32 v68, -v19, v194, v68
	v_fmac_f32_e32 v100, v19, v193
	v_fmac_f32_e32 v69, v20, v193
	v_fmac_f32_e32 v101, v20, v194
	v_fma_f32 v69, -v21, v194, v69
	v_fmac_f32_e32 v101, v21, v193
	v_fmac_f32_e32 v70, v14, v195
	v_fmac_f32_e32 v102, v14, v196
	v_fma_f32 v70, -v15, v196, v70
	v_fmac_f32_e32 v102, v15, v195
	v_fmac_f32_e32 v71, v16, v195
	v_fmac_f32_e32 v103, v16, v196
	v_fma_f32 v71, -v17, v196, v71
	v_fmac_f32_e32 v103, v17, v195
	v_fmac_f32_e32 v72, v18, v195
	v_fmac_f32_e32 v104, v18, v196
	v_fma_f32 v72, -v19, v196, v72
	v_fmac_f32_e32 v104, v19, v195
	v_fmac_f32_e32 v73, v20, v195
	v_fmac_f32_e32 v105, v20, v196
	v_fma_f32 v73, -v21, v196, v73
	v_fmac_f32_e32 v105, v21, v195
	v_fmac_f32_e32 v74, v14, v197
	v_fmac_f32_e32 v106, v14, v198
	v_fma_f32 v74, -v15, v198, v74
	v_fmac_f32_e32 v106, v15, v197
	v_fmac_f32_e32 v75, v16, v197
	v_fmac_f32_e32 v107, v16, v198
	v_fma_f32 v75, -v17, v198, v75
	v_fmac_f32_e32 v107, v17, v197
	v_fmac_f32_e32 v76, v18, v197
	v_fmac_f32_e32 v108, v18, v198
	v_fma_f32 v76, -v19, v198, v76
	v_fmac_f32_e32 v108, v19, v197
	v_fmac_f32_e32 v77, v20, v197
	v_fmac_f32_e32 v109, v20, v198
	v_fma_f32 v77, -v21, v198, v77
	v_fmac_f32_e32 v109, v21, v197
	v_cvt_pk_bf16_f32 v216, v46, v47
	v_cvt_pk_bf16_f32 v217, v48, v49
	ds_write_b64 v200, v[216:217] offset:0
	v_cvt_pk_bf16_f32 v218, v50, v51
	v_cvt_pk_bf16_f32 v219, v52, v53
	ds_write_b64 v200, v[218:219] offset:16
	v_cvt_pk_bf16_f32 v220, v54, v55
	v_cvt_pk_bf16_f32 v221, v56, v57
	ds_write_b64 v200, v[220:221] offset:32
	v_cvt_pk_bf16_f32 v222, v58, v59
	v_cvt_pk_bf16_f32 v223, v60, v61
	ds_write_b64 v200, v[222:223] offset:48
	v_cvt_pk_bf16_f32 v224, v62, v63
	v_cvt_pk_bf16_f32 v225, v64, v65
	ds_write_b64 v200, v[224:225] offset:2304
	v_cvt_pk_bf16_f32 v226, v66, v67
	v_cvt_pk_bf16_f32 v227, v68, v69
	ds_write_b64 v200, v[226:227] offset:2320
	v_cvt_pk_bf16_f32 v228, v70, v71
	v_cvt_pk_bf16_f32 v229, v72, v73
	ds_write_b64 v200, v[228:229] offset:2336
	v_cvt_pk_bf16_f32 v230, v74, v75
	v_cvt_pk_bf16_f32 v231, v76, v77
	ds_write_b64 v200, v[230:231] offset:2352
	v_cvt_pk_bf16_f32 v232, v78, v79
	v_cvt_pk_bf16_f32 v233, v80, v81
	ds_write_b64 v200, v[232:233] offset:4608
	v_cvt_pk_bf16_f32 v234, v82, v83
	v_cvt_pk_bf16_f32 v235, v84, v85
	ds_write_b64 v200, v[234:235] offset:4624
	v_cvt_pk_bf16_f32 v236, v86, v87
	v_cvt_pk_bf16_f32 v237, v88, v89
	ds_write_b64 v200, v[236:237] offset:4640
	v_cvt_pk_bf16_f32 v238, v90, v91
	v_cvt_pk_bf16_f32 v239, v92, v93
	ds_write_b64 v200, v[238:239] offset:4656
	v_cvt_pk_bf16_f32 v240, v94, v95
	v_cvt_pk_bf16_f32 v241, v96, v97
	ds_write_b64 v200, v[240:241] offset:6912
	v_cvt_pk_bf16_f32 v242, v98, v99
	v_cvt_pk_bf16_f32 v243, v100, v101
	ds_write_b64 v200, v[242:243] offset:6928
	v_cvt_pk_bf16_f32 v244, v102, v103
	v_cvt_pk_bf16_f32 v245, v104, v105
	ds_write_b64 v200, v[244:245] offset:6944
	v_cvt_pk_bf16_f32 v246, v106, v107
	v_cvt_pk_bf16_f32 v247, v108, v109
	ds_write_b64 v200, v[246:247] offset:6960
	s_waitcnt lgkmcnt(0)
	ds_read_b64_tr_b16 v[216:217], v201 offset:0
	ds_read_b64_tr_b16 v[218:219], v201 offset:288
	ds_read_b64_tr_b16 v[220:221], v201 offset:1152
	ds_read_b64_tr_b16 v[222:223], v201 offset:1440
	ds_read_b64_tr_b16 v[224:225], v201 offset:2304
	ds_read_b64_tr_b16 v[226:227], v201 offset:2592
	ds_read_b64_tr_b16 v[228:229], v201 offset:3456
	ds_read_b64_tr_b16 v[230:231], v201 offset:3744
	ds_read_b64_tr_b16 v[232:233], v201 offset:4608
	ds_read_b64_tr_b16 v[234:235], v201 offset:4896
	ds_read_b64_tr_b16 v[236:237], v201 offset:5760
	ds_read_b64_tr_b16 v[238:239], v201 offset:6048
	ds_read_b64_tr_b16 v[240:241], v201 offset:6912
	ds_read_b64_tr_b16 v[242:243], v201 offset:7200
	ds_read_b64_tr_b16 v[244:245], v201 offset:8064
	ds_read_b64_tr_b16 v[246:247], v201 offset:8352
	s_waitcnt lgkmcnt(14)
	v_mfma_f32_32x32x16_bf16 v[110:125], v[216:219], v[134:137], v[110:125]
	s_waitcnt lgkmcnt(12)
	v_mfma_f32_32x32x16_bf16 v[110:125], v[220:223], v[138:141], v[110:125]
	s_waitcnt lgkmcnt(10)
	v_mfma_f32_32x32x16_bf16 v[110:125], v[224:227], v[142:145], v[110:125]
	s_waitcnt lgkmcnt(8)
	v_mfma_f32_32x32x16_bf16 v[110:125], v[228:231], v[146:149], v[110:125]
	s_waitcnt lgkmcnt(6)
	v_mfma_f32_32x32x16_bf16 v[110:125], v[232:235], v[150:153], v[110:125]
	s_waitcnt lgkmcnt(4)
	v_mfma_f32_32x32x16_bf16 v[110:125], v[236:239], v[154:157], v[110:125]
	s_waitcnt lgkmcnt(2)
	v_mfma_f32_32x32x16_bf16 v[110:125], v[240:243], v[158:161], v[110:125]
	s_waitcnt lgkmcnt(0)
	v_mfma_f32_32x32x16_bf16 v[110:125], v[244:247], v[162:165], v[110:125]
	s_nop 7
	s_nop 3
	s_mov_b64 exec, s[44:45]
	ds_write_b32 v202, v110 offset:0
	ds_write_b32 v202, v111 offset:64
	ds_write_b32 v202, v112 offset:128
	ds_write_b32 v202, v113 offset:192
	ds_write_b32 v202, v114 offset:512
	ds_write_b32 v202, v115 offset:576
	ds_write_b32 v202, v116 offset:640
	ds_write_b32 v202, v117 offset:704
	ds_write_b32 v202, v118 offset:1024
	ds_write_b32 v202, v119 offset:1088
	ds_write_b32 v202, v120 offset:1152
	ds_write_b32 v202, v121 offset:1216
	ds_write_b32 v202, v122 offset:1536
	ds_write_b32 v202, v123 offset:1600
	ds_write_b32 v202, v124 offset:1664
	ds_write_b32 v202, v125 offset:1728
	s_mov_b64 exec, -1
	s_waitcnt lgkmcnt(0)
	ds_read_b128 v[216:219], v203
	ds_read_b128 v[220:223], v203 offset:16
	s_waitcnt lgkmcnt(0)
	v_mul_f32_e32 v224, 0x3d372713, v216
	v_mul_f32_e32 v225, 0x3d372713, v217
	v_mul_f32_e32 v226, 0x3d372713, v218
	v_mul_f32_e32 v227, 0x3d372713, v219
	v_mul_f32_e32 v228, 0x3d372713, v220
	v_mul_f32_e32 v229, 0x3d372713, v221
	v_mul_f32_e32 v230, 0x3d372713, v222
	v_mul_f32_e32 v231, 0x3d372713, v223
	v_mul_f32_e32 v224, v216, v224
	v_mul_f32_e32 v225, v217, v225
	v_mul_f32_e32 v226, v218, v226
	v_mul_f32_e32 v227, v219, v227
	v_mul_f32_e32 v228, v220, v228
	v_mul_f32_e32 v229, v221, v229
	v_mul_f32_e32 v230, v222, v230
	v_mul_f32_e32 v231, v223, v231
	v_fma_f32 v224, v216, v224, v216
	v_fma_f32 v225, v217, v225, v217
	v_fma_f32 v226, v218, v226, v218
	v_fma_f32 v227, v219, v227, v219
	v_fma_f32 v228, v220, v228, v220
	v_fma_f32 v229, v221, v229, v221
	v_fma_f32 v230, v222, v230, v222
	v_fma_f32 v231, v223, v231, v223
	v_mul_f32_e32 v224, 0x3f4c422a, v224
	v_mul_f32_e32 v225, 0x3f4c422a, v225
	v_mul_f32_e32 v226, 0x3f4c422a, v226
	v_mul_f32_e32 v227, 0x3f4c422a, v227
	v_mul_f32_e32 v228, 0x3f4c422a, v228
	v_mul_f32_e32 v229, 0x3f4c422a, v229
	v_mul_f32_e32 v230, 0x3f4c422a, v230
	v_mul_f32_e32 v231, 0x3f4c422a, v231
	v_add_f32_e32 v224, v224, v224
	v_add_f32_e32 v225, v225, v225
	v_add_f32_e32 v226, v226, v226
	v_add_f32_e32 v227, v227, v227
	v_add_f32_e32 v228, v228, v228
	v_add_f32_e32 v229, v229, v229
	v_add_f32_e32 v230, v230, v230
	v_add_f32_e32 v231, v231, v231
	v_mul_f32_e32 v224, 0xbfb8aa3b, v224
	v_mul_f32_e32 v225, 0xbfb8aa3b, v225
	v_mul_f32_e32 v226, 0xbfb8aa3b, v226
	v_mul_f32_e32 v227, 0xbfb8aa3b, v227
	v_mul_f32_e32 v228, 0xbfb8aa3b, v228
	v_mul_f32_e32 v229, 0xbfb8aa3b, v229
	v_mul_f32_e32 v230, 0xbfb8aa3b, v230
	v_mul_f32_e32 v231, 0xbfb8aa3b, v231
	v_exp_f32_e32 v224, v224
	v_exp_f32_e32 v225, v225
	v_exp_f32_e32 v226, v226
	v_exp_f32_e32 v227, v227
	v_exp_f32_e32 v228, v228
	v_exp_f32_e32 v229, v229
	v_exp_f32_e32 v230, v230
	v_exp_f32_e32 v231, v231
	s_nop 0
	v_add_f32_e32 v224, 1.0, v224
	v_add_f32_e32 v225, 1.0, v225
	v_add_f32_e32 v226, 1.0, v226
	v_add_f32_e32 v227, 1.0, v227
	v_add_f32_e32 v228, 1.0, v228
	v_add_f32_e32 v229, 1.0, v229
	v_add_f32_e32 v230, 1.0, v230
	v_add_f32_e32 v231, 1.0, v231
	v_rcp_f32_e32 v224, v224
	v_rcp_f32_e32 v225, v225
	v_rcp_f32_e32 v226, v226
	v_rcp_f32_e32 v227, v227
	v_rcp_f32_e32 v228, v228
	v_rcp_f32_e32 v229, v229
	v_rcp_f32_e32 v230, v230
	v_rcp_f32_e32 v231, v231
	s_nop 0
	v_mul_f32_e32 v224, v216, v224
	v_mul_f32_e32 v225, v217, v225
	v_mul_f32_e32 v226, v218, v226
	v_mul_f32_e32 v227, v219, v227
	v_mul_f32_e32 v228, v220, v228
	v_mul_f32_e32 v229, v221, v229
	v_mul_f32_e32 v230, v222, v230
	v_mul_f32_e32 v231, v223, v231
	v_cvt_pk_bf16_f32 v232, v224, v225
	v_cvt_pk_bf16_f32 v233, v226, v227
	v_cvt_pk_bf16_f32 v234, v228, v229
	v_cvt_pk_bf16_f32 v235, v230, v231
	s_add_u32 s70, s60, 0x20000
	s_addc_u32 s71, s61, 0
	global_store_dwordx4 v205, v[232:235], s[70:71]
	s_waitcnt vmcnt(1)
	v_mfma_f32_32x32x16_bf16 v[46:61], v[126:129], v[26:29], 0
	v_mfma_f32_32x32x16_bf16 v[78:93], v[126:129], v[34:37], 0
	v_mfma_f32_32x32x16_bf16 v[62:77], v[126:129], v[30:33], 0
	v_mfma_f32_32x32x16_bf16 v[94:109], v[126:129], v[38:41], 0
	v_mfma_f32_32x32x16_bf16 v[110:125], v[126:129], v[42:45], 0
	s_add_u32 s70, s58, 0x60000
	s_addc_u32 s71, s59, 0
	global_load_dwordx4 v[130:133], v204, s[70:71]
	s_nop 7
	s_nop 1
	v_fmac_f32_e32 v47, v6, v46
	v_fmac_f32_e32 v79, v6, v78
	v_fma_f32 v47, -v7, v78, v47
	v_fmac_f32_e32 v79, v7, v46
	v_fmac_f32_e32 v51, v6, v50
	v_fmac_f32_e32 v83, v6, v82
	v_fma_f32 v51, -v7, v82, v51
	v_fmac_f32_e32 v83, v7, v50
	v_fmac_f32_e32 v55, v6, v54
	v_fmac_f32_e32 v87, v6, v86
	v_fma_f32 v55, -v7, v86, v55
	v_fmac_f32_e32 v87, v7, v54
	v_fmac_f32_e32 v59, v6, v58
	v_fmac_f32_e32 v91, v6, v90
	v_fma_f32 v59, -v7, v90, v59
	v_fmac_f32_e32 v91, v7, v58
	v_fmac_f32_e32 v63, v14, v62
	v_fmac_f32_e32 v95, v14, v94
	v_fma_f32 v63, -v15, v94, v63
	v_fmac_f32_e32 v95, v15, v62
	v_fmac_f32_e32 v67, v14, v66
	v_fmac_f32_e32 v99, v14, v98
	v_fma_f32 v67, -v15, v98, v67
	v_fmac_f32_e32 v99, v15, v66
	v_fmac_f32_e32 v71, v14, v70
	v_fmac_f32_e32 v103, v14, v102
	v_fma_f32 v71, -v15, v102, v71
	v_fmac_f32_e32 v103, v15, v70
	v_fmac_f32_e32 v75, v14, v74
	v_fmac_f32_e32 v107, v14, v106
	v_fma_f32 v75, -v15, v106, v75
	v_fmac_f32_e32 v107, v15, v74
	v_fmac_f32_e32 v48, v6, v47
	v_fmac_f32_e32 v80, v6, v79
	v_fma_f32 v48, -v7, v79, v48
	v_fmac_f32_e32 v80, v7, v47
	v_fmac_f32_e32 v52, v6, v51
	v_fmac_f32_e32 v84, v6, v83
	v_fma_f32 v52, -v7, v83, v52
	v_fmac_f32_e32 v84, v7, v51
	v_fmac_f32_e32 v56, v6, v55
	v_fmac_f32_e32 v88, v6, v87
	v_fma_f32 v56, -v7, v87, v56
	v_fmac_f32_e32 v88, v7, v55
	v_fmac_f32_e32 v60, v6, v59
	v_fmac_f32_e32 v92, v6, v91
	v_fma_f32 v60, -v7, v91, v60
	v_fmac_f32_e32 v92, v7, v59
	v_fmac_f32_e32 v64, v14, v63
	v_fmac_f32_e32 v96, v14, v95
	v_fma_f32 v64, -v15, v95, v64
	v_fmac_f32_e32 v96, v15, v63
	v_fmac_f32_e32 v68, v14, v67
	v_fmac_f32_e32 v100, v14, v99
	v_fma_f32 v68, -v15, v99, v68
	v_fmac_f32_e32 v100, v15, v67
	v_fmac_f32_e32 v72, v14, v71
	v_fmac_f32_e32 v104, v14, v103
	v_fma_f32 v72, -v15, v103, v72
	v_fmac_f32_e32 v104, v15, v71
	v_fmac_f32_e32 v76, v14, v75
	v_fmac_f32_e32 v108, v14, v107
	v_fma_f32 v76, -v15, v107, v76
	v_fmac_f32_e32 v108, v15, v75
	v_fmac_f32_e32 v49, v6, v48
	v_fmac_f32_e32 v81, v6, v80
	v_fma_f32 v49, -v7, v80, v49
	v_fmac_f32_e32 v81, v7, v48
	v_fmac_f32_e32 v53, v6, v52
	v_fmac_f32_e32 v85, v6, v84
	v_fma_f32 v53, -v7, v84, v53
	v_fmac_f32_e32 v85, v7, v52
	v_fmac_f32_e32 v57, v6, v56
	v_fmac_f32_e32 v89, v6, v88
	v_fma_f32 v57, -v7, v88, v57
	v_fmac_f32_e32 v89, v7, v56
	v_fmac_f32_e32 v61, v6, v60
	v_fmac_f32_e32 v93, v6, v92
	v_fma_f32 v61, -v7, v92, v61
	v_fmac_f32_e32 v93, v7, v60
	v_fmac_f32_e32 v65, v14, v64
	v_fmac_f32_e32 v97, v14, v96
	v_fma_f32 v65, -v15, v96, v65
	v_fmac_f32_e32 v97, v15, v64
	v_fmac_f32_e32 v69, v14, v68
	v_fmac_f32_e32 v101, v14, v100
	v_fma_f32 v69, -v15, v100, v69
	v_fmac_f32_e32 v101, v15, v68
	v_fmac_f32_e32 v73, v14, v72
	v_fmac_f32_e32 v105, v14, v104
	v_fma_f32 v73, -v15, v104, v73
	v_fmac_f32_e32 v105, v15, v72
	v_fmac_f32_e32 v77, v14, v76
	v_fmac_f32_e32 v109, v14, v108
	v_fma_f32 v77, -v15, v108, v77
	v_fmac_f32_e32 v109, v15, v76
	ds_bpermute_b32 v167, v199, v49
	ds_bpermute_b32 v168, v199, v81
	ds_bpermute_b32 v169, v199, v53
	ds_bpermute_b32 v170, v199, v85
	ds_bpermute_b32 v171, v199, v57
	ds_bpermute_b32 v172, v199, v89
	ds_bpermute_b32 v173, v199, v61
	ds_bpermute_b32 v174, v199, v93
	ds_bpermute_b32 v175, v199, v65
	ds_bpermute_b32 v176, v199, v97
	ds_bpermute_b32 v177, v199, v69
	ds_bpermute_b32 v178, v199, v101
	ds_bpermute_b32 v179, v199, v73
	ds_bpermute_b32 v180, v199, v105
	ds_bpermute_b32 v181, v199, v77
	ds_bpermute_b32 v182, v199, v109
	s_waitcnt lgkmcnt(0)
	v_cndmask_b32_e64 v216, v49, v167, s[40:41]
	v_cndmask_b32_e64 v217, v81, v168, s[40:41]
	v_cndmask_b32_e64 v218, v167, v49, s[40:41]
	v_cndmask_b32_e64 v219, v168, v81, s[40:41]
	v_fma_f32 v213, v12, v22, v216
	v_fma_f32 v214, v12, v23, v217
	v_fma_f32 v213, -v13, v23, v213
	v_fmac_f32_e32 v214, v13, v22
	v_fma_f32 v215, v12, v213, v218
	v_fma_f32 v248, v12, v214, v219
	v_fma_f32 v215, -v13, v214, v215
	v_fmac_f32_e32 v248, v13, v213
	v_cndmask_b32_e64 v183, v22, v213, s[40:41]
	v_cndmask_b32_e64 v184, v23, v214, s[40:41]
	v_cndmask_b32_e64 v224, v65, v175, s[40:41]
	v_cndmask_b32_e64 v225, v97, v176, s[40:41]
	v_cndmask_b32_e64 v226, v175, v65, s[40:41]
	v_cndmask_b32_e64 v227, v176, v97, s[40:41]
	v_fma_f32 v251, v20, v24, v224
	v_fma_f32 v252, v20, v25, v225
	v_fma_f32 v251, -v21, v25, v251
	v_fmac_f32_e32 v252, v21, v24
	v_fma_f32 v253, v20, v251, v226
	v_fma_f32 v211, v20, v252, v227
	v_fma_f32 v253, -v21, v252, v253
	v_fmac_f32_e32 v211, v21, v251
	v_cndmask_b32_e64 v191, v24, v251, s[40:41]
	v_cndmask_b32_e64 v192, v25, v252, s[40:41]
	v_cndmask_b32_e64 v216, v53, v169, s[40:41]
	v_cndmask_b32_e64 v217, v85, v170, s[40:41]
	v_cndmask_b32_e64 v218, v169, v53, s[40:41]
	v_cndmask_b32_e64 v219, v170, v85, s[40:41]
	v_fma_f32 v249, v12, v215, v216
	v_fma_f32 v250, v12, v248, v217
	v_fma_f32 v249, -v13, v248, v249
	v_fmac_f32_e32 v250, v13, v215
	v_fma_f32 v213, v12, v249, v218
	v_fma_f32 v214, v12, v250, v219
	v_fma_f32 v213, -v13, v250, v213
	v_fmac_f32_e32 v214, v13, v249
	v_cndmask_b32_e64 v185, v215, v249, s[40:41]
	v_cndmask_b32_e64 v186, v248, v250, s[40:41]
	v_cndmask_b32_e64 v224, v69, v177, s[40:41]
	v_cndmask_b32_e64 v225, v101, v178, s[40:41]
	v_cndmask_b32_e64 v226, v177, v69, s[40:41]
	v_cndmask_b32_e64 v227, v178, v101, s[40:41]
	v_fma_f32 v212, v20, v253, v224
	v_fma_f32 v209, v20, v211, v225
	v_fma_f32 v212, -v21, v211, v212
	v_fmac_f32_e32 v209, v21, v253
	v_fma_f32 v251, v20, v212, v226
	v_fma_f32 v252, v20, v209, v227
	v_fma_f32 v251, -v21, v209, v251
	v_fmac_f32_e32 v252, v21, v212
	v_cndmask_b32_e64 v193, v253, v212, s[40:41]
	v_cndmask_b32_e64 v194, v211, v209, s[40:41]
	v_cndmask_b32_e64 v216, v57, v171, s[40:41]
	v_cndmask_b32_e64 v217, v89, v172, s[40:41]
	v_cndmask_b32_e64 v218, v171, v57, s[40:41]
	v_cndmask_b32_e64 v219, v172, v89, s[40:41]
	v_fma_f32 v215, v12, v213, v216
	v_fma_f32 v248, v12, v214, v217
	v_fma_f32 v215, -v13, v214, v215
	v_fmac_f32_e32 v248, v13, v213
	v_fma_f32 v249, v12, v215, v218
	v_fma_f32 v250, v12, v248, v219
	v_fma_f32 v249, -v13, v248, v249
	v_fmac_f32_e32 v250, v13, v215
	v_cndmask_b32_e64 v187, v213, v215, s[40:41]
	v_cndmask_b32_e64 v188, v214, v248, s[40:41]
	v_cndmask_b32_e64 v224, v73, v179, s[40:41]
	v_cndmask_b32_e64 v225, v105, v180, s[40:41]
	v_cndmask_b32_e64 v226, v179, v73, s[40:41]
	v_cndmask_b32_e64 v227, v180, v105, s[40:41]
	v_fma_f32 v253, v20, v251, v224
	v_fma_f32 v211, v20, v252, v225
	v_fma_f32 v253, -v21, v252, v253
	v_fmac_f32_e32 v211, v21, v251
	v_fma_f32 v212, v20, v253, v226
	v_fma_f32 v209, v20, v211, v227
	v_fma_f32 v212, -v21, v211, v212
	v_fmac_f32_e32 v209, v21, v253
	v_cndmask_b32_e64 v195, v251, v253, s[40:41]
	v_cndmask_b32_e64 v196, v252, v211, s[40:41]
	v_cndmask_b32_e64 v216, v61, v173, s[40:41]
	v_cndmask_b32_e64 v217, v93, v174, s[40:41]
	v_cndmask_b32_e64 v218, v173, v61, s[40:41]
	v_cndmask_b32_e64 v219, v174, v93, s[40:41]
	v_fma_f32 v213, v12, v249, v216
	v_fma_f32 v214, v12, v250, v217
	v_fma_f32 v213, -v13, v250, v213
	v_fmac_f32_e32 v214, v13, v249
	v_fma_f32 v215, v12, v213, v218
	v_fma_f32 v248, v12, v214, v219
	v_fma_f32 v215, -v13, v214, v215
	v_fmac_f32_e32 v248, v13, v213
	v_cndmask_b32_e64 v189, v249, v213, s[40:41]
	v_cndmask_b32_e64 v190, v250, v214, s[40:41]
	v_cndmask_b32_e64 v224, v77, v181, s[40:41]
	v_cndmask_b32_e64 v225, v109, v182, s[40:41]
	v_cndmask_b32_e64 v226, v181, v77, s[40:41]
	v_cndmask_b32_e64 v227, v182, v109, s[40:41]
	v_fma_f32 v251, v20, v212, v224
	v_fma_f32 v252, v20, v209, v225
	v_fma_f32 v251, -v21, v209, v251
	v_fmac_f32_e32 v252, v21, v212
	v_fma_f32 v253, v20, v251, v226
	v_fma_f32 v211, v20, v252, v227
	v_fma_f32 v253, -v21, v252, v253
	v_fmac_f32_e32 v211, v21, v251
	v_cndmask_b32_e64 v197, v212, v251, s[40:41]
	v_cndmask_b32_e64 v198, v209, v252, s[40:41]
	v_mov_b32_e32 v22, v215
	v_mov_b32_e32 v23, v248
	v_mov_b32_e32 v24, v253
	v_mov_b32_e32 v25, v211
	v_fmac_f32_e32 v46, v6, v183
	v_fmac_f32_e32 v78, v6, v184
	v_fma_f32 v46, -v7, v184, v46
	v_fmac_f32_e32 v78, v7, v183
	v_fmac_f32_e32 v47, v8, v183
	v_fmac_f32_e32 v79, v8, v184
	v_fma_f32 v47, -v9, v184, v47
	v_fmac_f32_e32 v79, v9, v183
	v_fmac_f32_e32 v48, v10, v183
	v_fmac_f32_e32 v80, v10, v184
	v_fma_f32 v48, -v11, v184, v48
	v_fmac_f32_e32 v80, v11, v183
	v_fmac_f32_e32 v49, v12, v183
	v_fmac_f32_e32 v81, v12, v184
	v_fma_f32 v49, -v13, v184, v49
	v_fmac_f32_e32 v81, v13, v183
	v_fmac_f32_e32 v50, v6, v185
	v_fmac_f32_e32 v82, v6, v186
	v_fma_f32 v50, -v7, v186, v50
	v_fmac_f32_e32 v82, v7, v185
	v_fmac_f32_e32 v51, v8, v185
	v_fmac_f32_e32 v83, v8, v186
	v_fma_f32 v51, -v9, v186, v51
	v_fmac_f32_e32 v83, v9, v185
	v_fmac_f32_e32 v52, v10, v185
	v_fmac_f32_e32 v84, v10, v186
	v_fma_f32 v52, -v11, v186, v52
	v_fmac_f32_e32 v84, v11, v185
	v_fmac_f32_e32 v53, v12, v185
	v_fmac_f32_e32 v85, v12, v186
	v_fma_f32 v53, -v13, v186, v53
	v_fmac_f32_e32 v85, v13, v185
	v_fmac_f32_e32 v54, v6, v187
	v_fmac_f32_e32 v86, v6, v188
	v_fma_f32 v54, -v7, v188, v54
	v_fmac_f32_e32 v86, v7, v187
	v_fmac_f32_e32 v55, v8, v187
	v_fmac_f32_e32 v87, v8, v188
	v_fma_f32 v55, -v9, v188, v55
	v_fmac_f32_e32 v87, v9, v187
	v_fmac_f32_e32 v56, v10, v187
	v_fmac_f32_e32 v88, v10, v188
	v_fma_f32 v56, -v11, v188, v56
	v_fmac_f32_e32 v88, v11, v187
	v_fmac_f32_e32 v57, v12, v187
	v_fmac_f32_e32 v89, v12, v188
	v_fma_f32 v57, -v13, v188, v57
	v_fmac_f32_e32 v89, v13, v187
	v_fmac_f32_e32 v58, v6, v189
	v_fmac_f32_e32 v90, v6, v190
	v_fma_f32 v58, -v7, v190, v58
	v_fmac_f32_e32 v90, v7, v189
	v_fmac_f32_e32 v59, v8, v189
	v_fmac_f32_e32 v91, v8, v190
	v_fma_f32 v59, -v9, v190, v59
	v_fmac_f32_e32 v91, v9, v189
	v_fmac_f32_e32 v60, v10, v189
	v_fmac_f32_e32 v92, v10, v190
	v_fma_f32 v60, -v11, v190, v60
	v_fmac_f32_e32 v92, v11, v189
	v_fmac_f32_e32 v61, v12, v189
	v_fmac_f32_e32 v93, v12, v190
	v_fma_f32 v61, -v13, v190, v61
	v_fmac_f32_e32 v93, v13, v189
	v_fmac_f32_e32 v62, v14, v191
	v_fmac_f32_e32 v94, v14, v192
	v_fma_f32 v62, -v15, v192, v62
	v_fmac_f32_e32 v94, v15, v191
	v_fmac_f32_e32 v63, v16, v191
	v_fmac_f32_e32 v95, v16, v192
	v_fma_f32 v63, -v17, v192, v63
	v_fmac_f32_e32 v95, v17, v191
	v_fmac_f32_e32 v64, v18, v191
	v_fmac_f32_e32 v96, v18, v192
	v_fma_f32 v64, -v19, v192, v64
	v_fmac_f32_e32 v96, v19, v191
	v_fmac_f32_e32 v65, v20, v191
	v_fmac_f32_e32 v97, v20, v192
	v_fma_f32 v65, -v21, v192, v65
	v_fmac_f32_e32 v97, v21, v191
	v_fmac_f32_e32 v66, v14, v193
	v_fmac_f32_e32 v98, v14, v194
	v_fma_f32 v66, -v15, v194, v66
	v_fmac_f32_e32 v98, v15, v193
	v_fmac_f32_e32 v67, v16, v193
	v_fmac_f32_e32 v99, v16, v194
	v_fma_f32 v67, -v17, v194, v67
	v_fmac_f32_e32 v99, v17, v193
	v_fmac_f32_e32 v68, v18, v193
	v_fmac_f32_e32 v100, v18, v194
	v_fma_f32 v68, -v19, v194, v68
	v_fmac_f32_e32 v100, v19, v193
	v_fmac_f32_e32 v69, v20, v193
	v_fmac_f32_e32 v101, v20, v194
	v_fma_f32 v69, -v21, v194, v69
	v_fmac_f32_e32 v101, v21, v193
	v_fmac_f32_e32 v70, v14, v195
	v_fmac_f32_e32 v102, v14, v196
	v_fma_f32 v70, -v15, v196, v70
	v_fmac_f32_e32 v102, v15, v195
	v_fmac_f32_e32 v71, v16, v195
	v_fmac_f32_e32 v103, v16, v196
	v_fma_f32 v71, -v17, v196, v71
	v_fmac_f32_e32 v103, v17, v195
	v_fmac_f32_e32 v72, v18, v195
	v_fmac_f32_e32 v104, v18, v196
	v_fma_f32 v72, -v19, v196, v72
	v_fmac_f32_e32 v104, v19, v195
	v_fmac_f32_e32 v73, v20, v195
	v_fmac_f32_e32 v105, v20, v196
	v_fma_f32 v73, -v21, v196, v73
	v_fmac_f32_e32 v105, v21, v195
	v_fmac_f32_e32 v74, v14, v197
	v_fmac_f32_e32 v106, v14, v198
	v_fma_f32 v74, -v15, v198, v74
	v_fmac_f32_e32 v106, v15, v197
	v_fmac_f32_e32 v75, v16, v197
	v_fmac_f32_e32 v107, v16, v198
	v_fma_f32 v75, -v17, v198, v75
	v_fmac_f32_e32 v107, v17, v197
	v_fmac_f32_e32 v76, v18, v197
	v_fmac_f32_e32 v108, v18, v198
	v_fma_f32 v76, -v19, v198, v76
	v_fmac_f32_e32 v108, v19, v197
	v_fmac_f32_e32 v77, v20, v197
	v_fmac_f32_e32 v109, v20, v198
	v_fma_f32 v77, -v21, v198, v77
	v_fmac_f32_e32 v109, v21, v197
	v_cvt_pk_bf16_f32 v216, v46, v47
	v_cvt_pk_bf16_f32 v217, v48, v49
	ds_write_b64 v200, v[216:217] offset:0
	v_cvt_pk_bf16_f32 v218, v50, v51
	v_cvt_pk_bf16_f32 v219, v52, v53
	ds_write_b64 v200, v[218:219] offset:16
	v_cvt_pk_bf16_f32 v220, v54, v55
	v_cvt_pk_bf16_f32 v221, v56, v57
	ds_write_b64 v200, v[220:221] offset:32
	v_cvt_pk_bf16_f32 v222, v58, v59
	v_cvt_pk_bf16_f32 v223, v60, v61
	ds_write_b64 v200, v[222:223] offset:48
	v_cvt_pk_bf16_f32 v224, v62, v63
	v_cvt_pk_bf16_f32 v225, v64, v65
	ds_write_b64 v200, v[224:225] offset:2304
	v_cvt_pk_bf16_f32 v226, v66, v67
	v_cvt_pk_bf16_f32 v227, v68, v69
	ds_write_b64 v200, v[226:227] offset:2320
	v_cvt_pk_bf16_f32 v228, v70, v71
	v_cvt_pk_bf16_f32 v229, v72, v73
	ds_write_b64 v200, v[228:229] offset:2336
	v_cvt_pk_bf16_f32 v230, v74, v75
	v_cvt_pk_bf16_f32 v231, v76, v77
	ds_write_b64 v200, v[230:231] offset:2352
	v_cvt_pk_bf16_f32 v232, v78, v79
	v_cvt_pk_bf16_f32 v233, v80, v81
	ds_write_b64 v200, v[232:233] offset:4608
	v_cvt_pk_bf16_f32 v234, v82, v83
	v_cvt_pk_bf16_f32 v235, v84, v85
	ds_write_b64 v200, v[234:235] offset:4624
	v_cvt_pk_bf16_f32 v236, v86, v87
	v_cvt_pk_bf16_f32 v237, v88, v89
	ds_write_b64 v200, v[236:237] offset:4640
	v_cvt_pk_bf16_f32 v238, v90, v91
	v_cvt_pk_bf16_f32 v239, v92, v93
	ds_write_b64 v200, v[238:239] offset:4656
	v_cvt_pk_bf16_f32 v240, v94, v95
	v_cvt_pk_bf16_f32 v241, v96, v97
	ds_write_b64 v200, v[240:241] offset:6912
	v_cvt_pk_bf16_f32 v242, v98, v99
	v_cvt_pk_bf16_f32 v243, v100, v101
	ds_write_b64 v200, v[242:243] offset:6928
	v_cvt_pk_bf16_f32 v244, v102, v103
	v_cvt_pk_bf16_f32 v245, v104, v105
	ds_write_b64 v200, v[244:245] offset:6944
	v_cvt_pk_bf16_f32 v246, v106, v107
	v_cvt_pk_bf16_f32 v247, v108, v109
	ds_write_b64 v200, v[246:247] offset:6960
	s_waitcnt lgkmcnt(0)
	ds_read_b64_tr_b16 v[216:217], v201 offset:0
	ds_read_b64_tr_b16 v[218:219], v201 offset:288
	ds_read_b64_tr_b16 v[220:221], v201 offset:1152
	ds_read_b64_tr_b16 v[222:223], v201 offset:1440
	ds_read_b64_tr_b16 v[224:225], v201 offset:2304
	ds_read_b64_tr_b16 v[226:227], v201 offset:2592
	ds_read_b64_tr_b16 v[228:229], v201 offset:3456
	ds_read_b64_tr_b16 v[230:231], v201 offset:3744
	ds_read_b64_tr_b16 v[232:233], v201 offset:4608
	ds_read_b64_tr_b16 v[234:235], v201 offset:4896
	ds_read_b64_tr_b16 v[236:237], v201 offset:5760
	ds_read_b64_tr_b16 v[238:239], v201 offset:6048
	ds_read_b64_tr_b16 v[240:241], v201 offset:6912
	ds_read_b64_tr_b16 v[242:243], v201 offset:7200
	ds_read_b64_tr_b16 v[244:245], v201 offset:8064
	ds_read_b64_tr_b16 v[246:247], v201 offset:8352
	s_waitcnt lgkmcnt(14)
	v_mfma_f32_32x32x16_bf16 v[110:125], v[216:219], v[134:137], v[110:125]
	s_waitcnt lgkmcnt(12)
	v_mfma_f32_32x32x16_bf16 v[110:125], v[220:223], v[138:141], v[110:125]
	s_waitcnt lgkmcnt(10)
	v_mfma_f32_32x32x16_bf16 v[110:125], v[224:227], v[142:145], v[110:125]
	s_waitcnt lgkmcnt(8)
	v_mfma_f32_32x32x16_bf16 v[110:125], v[228:231], v[146:149], v[110:125]
	s_waitcnt lgkmcnt(6)
	v_mfma_f32_32x32x16_bf16 v[110:125], v[232:235], v[150:153], v[110:125]
	s_waitcnt lgkmcnt(4)
	v_mfma_f32_32x32x16_bf16 v[110:125], v[236:239], v[154:157], v[110:125]
	s_waitcnt lgkmcnt(2)
	v_mfma_f32_32x32x16_bf16 v[110:125], v[240:243], v[158:161], v[110:125]
	s_waitcnt lgkmcnt(0)
	v_mfma_f32_32x32x16_bf16 v[110:125], v[244:247], v[162:165], v[110:125]
	s_nop 7
	s_nop 3
	s_mov_b64 exec, s[44:45]
	ds_write_b32 v202, v110 offset:0
	ds_write_b32 v202, v111 offset:64
	ds_write_b32 v202, v112 offset:128
	ds_write_b32 v202, v113 offset:192
	ds_write_b32 v202, v114 offset:512
	ds_write_b32 v202, v115 offset:576
	ds_write_b32 v202, v116 offset:640
	ds_write_b32 v202, v117 offset:704
	ds_write_b32 v202, v118 offset:1024
	ds_write_b32 v202, v119 offset:1088
	ds_write_b32 v202, v120 offset:1152
	ds_write_b32 v202, v121 offset:1216
	ds_write_b32 v202, v122 offset:1536
	ds_write_b32 v202, v123 offset:1600
	ds_write_b32 v202, v124 offset:1664
	ds_write_b32 v202, v125 offset:1728
	s_mov_b64 exec, -1
	s_waitcnt lgkmcnt(0)
	ds_read_b128 v[216:219], v203
	ds_read_b128 v[220:223], v203 offset:16
	s_waitcnt lgkmcnt(0)
	v_mul_f32_e32 v224, 0x3d372713, v216
	v_mul_f32_e32 v225, 0x3d372713, v217
	v_mul_f32_e32 v226, 0x3d372713, v218
	v_mul_f32_e32 v227, 0x3d372713, v219
	v_mul_f32_e32 v228, 0x3d372713, v220
	v_mul_f32_e32 v229, 0x3d372713, v221
	v_mul_f32_e32 v230, 0x3d372713, v222
	v_mul_f32_e32 v231, 0x3d372713, v223
	v_mul_f32_e32 v224, v216, v224
	v_mul_f32_e32 v225, v217, v225
	v_mul_f32_e32 v226, v218, v226
	v_mul_f32_e32 v227, v219, v227
	v_mul_f32_e32 v228, v220, v228
	v_mul_f32_e32 v229, v221, v229
	v_mul_f32_e32 v230, v222, v230
	v_mul_f32_e32 v231, v223, v231
	v_fma_f32 v224, v216, v224, v216
	v_fma_f32 v225, v217, v225, v217
	v_fma_f32 v226, v218, v226, v218
	v_fma_f32 v227, v219, v227, v219
	v_fma_f32 v228, v220, v228, v220
	v_fma_f32 v229, v221, v229, v221
	v_fma_f32 v230, v222, v230, v222
	v_fma_f32 v231, v223, v231, v223
	v_mul_f32_e32 v224, 0x3f4c422a, v224
	v_mul_f32_e32 v225, 0x3f4c422a, v225
	v_mul_f32_e32 v226, 0x3f4c422a, v226
	v_mul_f32_e32 v227, 0x3f4c422a, v227
	v_mul_f32_e32 v228, 0x3f4c422a, v228
	v_mul_f32_e32 v229, 0x3f4c422a, v229
	v_mul_f32_e32 v230, 0x3f4c422a, v230
	v_mul_f32_e32 v231, 0x3f4c422a, v231
	v_add_f32_e32 v224, v224, v224
	v_add_f32_e32 v225, v225, v225
	v_add_f32_e32 v226, v226, v226
	v_add_f32_e32 v227, v227, v227
	v_add_f32_e32 v228, v228, v228
	v_add_f32_e32 v229, v229, v229
	v_add_f32_e32 v230, v230, v230
	v_add_f32_e32 v231, v231, v231
	v_mul_f32_e32 v224, 0xbfb8aa3b, v224
	v_mul_f32_e32 v225, 0xbfb8aa3b, v225
	v_mul_f32_e32 v226, 0xbfb8aa3b, v226
	v_mul_f32_e32 v227, 0xbfb8aa3b, v227
	v_mul_f32_e32 v228, 0xbfb8aa3b, v228
	v_mul_f32_e32 v229, 0xbfb8aa3b, v229
	v_mul_f32_e32 v230, 0xbfb8aa3b, v230
	v_mul_f32_e32 v231, 0xbfb8aa3b, v231
	v_exp_f32_e32 v224, v224
	v_exp_f32_e32 v225, v225
	v_exp_f32_e32 v226, v226
	v_exp_f32_e32 v227, v227
	v_exp_f32_e32 v228, v228
	v_exp_f32_e32 v229, v229
	v_exp_f32_e32 v230, v230
	v_exp_f32_e32 v231, v231
	s_nop 0
	v_add_f32_e32 v224, 1.0, v224
	v_add_f32_e32 v225, 1.0, v225
	v_add_f32_e32 v226, 1.0, v226
	v_add_f32_e32 v227, 1.0, v227
	v_add_f32_e32 v228, 1.0, v228
	v_add_f32_e32 v229, 1.0, v229
	v_add_f32_e32 v230, 1.0, v230
	v_add_f32_e32 v231, 1.0, v231
	v_rcp_f32_e32 v224, v224
	v_rcp_f32_e32 v225, v225
	v_rcp_f32_e32 v226, v226
	v_rcp_f32_e32 v227, v227
	v_rcp_f32_e32 v228, v228
	v_rcp_f32_e32 v229, v229
	v_rcp_f32_e32 v230, v230
	v_rcp_f32_e32 v231, v231
	s_nop 0
	v_mul_f32_e32 v224, v216, v224
	v_mul_f32_e32 v225, v217, v225
	v_mul_f32_e32 v226, v218, v226
	v_mul_f32_e32 v227, v219, v227
	v_mul_f32_e32 v228, v220, v228
	v_mul_f32_e32 v229, v221, v229
	v_mul_f32_e32 v230, v222, v230
	v_mul_f32_e32 v231, v223, v231
	v_cvt_pk_bf16_f32 v232, v224, v225
	v_cvt_pk_bf16_f32 v233, v226, v227
	v_cvt_pk_bf16_f32 v234, v228, v229
	v_cvt_pk_bf16_f32 v235, v230, v231
	s_add_u32 s70, s60, 0x40000
	s_addc_u32 s71, s61, 0
	global_store_dwordx4 v205, v[232:235], s[70:71]
	s_waitcnt vmcnt(1)
	v_mfma_f32_32x32x16_bf16 v[46:61], v[130:133], v[26:29], 0
	v_mfma_f32_32x32x16_bf16 v[78:93], v[130:133], v[34:37], 0
	v_mfma_f32_32x32x16_bf16 v[62:77], v[130:133], v[30:33], 0
	v_mfma_f32_32x32x16_bf16 v[94:109], v[130:133], v[38:41], 0
	v_mfma_f32_32x32x16_bf16 v[110:125], v[130:133], v[42:45], 0
	s_nop 7
	s_nop 1
	v_fmac_f32_e32 v47, v6, v46
	v_fmac_f32_e32 v79, v6, v78
	v_fma_f32 v47, -v7, v78, v47
	v_fmac_f32_e32 v79, v7, v46
	v_fmac_f32_e32 v51, v6, v50
	v_fmac_f32_e32 v83, v6, v82
	v_fma_f32 v51, -v7, v82, v51
	v_fmac_f32_e32 v83, v7, v50
	v_fmac_f32_e32 v55, v6, v54
	v_fmac_f32_e32 v87, v6, v86
	v_fma_f32 v55, -v7, v86, v55
	v_fmac_f32_e32 v87, v7, v54
	v_fmac_f32_e32 v59, v6, v58
	v_fmac_f32_e32 v91, v6, v90
	v_fma_f32 v59, -v7, v90, v59
	v_fmac_f32_e32 v91, v7, v58
	v_fmac_f32_e32 v63, v14, v62
	v_fmac_f32_e32 v95, v14, v94
	v_fma_f32 v63, -v15, v94, v63
	v_fmac_f32_e32 v95, v15, v62
	v_fmac_f32_e32 v67, v14, v66
	v_fmac_f32_e32 v99, v14, v98
	v_fma_f32 v67, -v15, v98, v67
	v_fmac_f32_e32 v99, v15, v66
	v_fmac_f32_e32 v71, v14, v70
	v_fmac_f32_e32 v103, v14, v102
	v_fma_f32 v71, -v15, v102, v71
	v_fmac_f32_e32 v103, v15, v70
	v_fmac_f32_e32 v75, v14, v74
	v_fmac_f32_e32 v107, v14, v106
	v_fma_f32 v75, -v15, v106, v75
	v_fmac_f32_e32 v107, v15, v74
	v_fmac_f32_e32 v48, v6, v47
	v_fmac_f32_e32 v80, v6, v79
	v_fma_f32 v48, -v7, v79, v48
	v_fmac_f32_e32 v80, v7, v47
	v_fmac_f32_e32 v52, v6, v51
	v_fmac_f32_e32 v84, v6, v83
	v_fma_f32 v52, -v7, v83, v52
	v_fmac_f32_e32 v84, v7, v51
	v_fmac_f32_e32 v56, v6, v55
	v_fmac_f32_e32 v88, v6, v87
	v_fma_f32 v56, -v7, v87, v56
	v_fmac_f32_e32 v88, v7, v55
	v_fmac_f32_e32 v60, v6, v59
	v_fmac_f32_e32 v92, v6, v91
	v_fma_f32 v60, -v7, v91, v60
	v_fmac_f32_e32 v92, v7, v59
	v_fmac_f32_e32 v64, v14, v63
	v_fmac_f32_e32 v96, v14, v95
	v_fma_f32 v64, -v15, v95, v64
	v_fmac_f32_e32 v96, v15, v63
	v_fmac_f32_e32 v68, v14, v67
	v_fmac_f32_e32 v100, v14, v99
	v_fma_f32 v68, -v15, v99, v68
	v_fmac_f32_e32 v100, v15, v67
	v_fmac_f32_e32 v72, v14, v71
	v_fmac_f32_e32 v104, v14, v103
	v_fma_f32 v72, -v15, v103, v72
	v_fmac_f32_e32 v104, v15, v71
	v_fmac_f32_e32 v76, v14, v75
	v_fmac_f32_e32 v108, v14, v107
	v_fma_f32 v76, -v15, v107, v76
	v_fmac_f32_e32 v108, v15, v75
	v_fmac_f32_e32 v49, v6, v48
	v_fmac_f32_e32 v81, v6, v80
	v_fma_f32 v49, -v7, v80, v49
	v_fmac_f32_e32 v81, v7, v48
	v_fmac_f32_e32 v53, v6, v52
	v_fmac_f32_e32 v85, v6, v84
	v_fma_f32 v53, -v7, v84, v53
	v_fmac_f32_e32 v85, v7, v52
	v_fmac_f32_e32 v57, v6, v56
	v_fmac_f32_e32 v89, v6, v88
	v_fma_f32 v57, -v7, v88, v57
	v_fmac_f32_e32 v89, v7, v56
	v_fmac_f32_e32 v61, v6, v60
	v_fmac_f32_e32 v93, v6, v92
	v_fma_f32 v61, -v7, v92, v61
	v_fmac_f32_e32 v93, v7, v60
	v_fmac_f32_e32 v65, v14, v64
	v_fmac_f32_e32 v97, v14, v96
	v_fma_f32 v65, -v15, v96, v65
	v_fmac_f32_e32 v97, v15, v64
	v_fmac_f32_e32 v69, v14, v68
	v_fmac_f32_e32 v101, v14, v100
	v_fma_f32 v69, -v15, v100, v69
	v_fmac_f32_e32 v101, v15, v68
	v_fmac_f32_e32 v73, v14, v72
	v_fmac_f32_e32 v105, v14, v104
	v_fma_f32 v73, -v15, v104, v73
	v_fmac_f32_e32 v105, v15, v72
	v_fmac_f32_e32 v77, v14, v76
	v_fmac_f32_e32 v109, v14, v108
	v_fma_f32 v77, -v15, v108, v77
	v_fmac_f32_e32 v109, v15, v76
	ds_bpermute_b32 v167, v199, v49
	ds_bpermute_b32 v168, v199, v81
	ds_bpermute_b32 v169, v199, v53
	ds_bpermute_b32 v170, v199, v85
	ds_bpermute_b32 v171, v199, v57
	ds_bpermute_b32 v172, v199, v89
	ds_bpermute_b32 v173, v199, v61
	ds_bpermute_b32 v174, v199, v93
	ds_bpermute_b32 v175, v199, v65
	ds_bpermute_b32 v176, v199, v97
	ds_bpermute_b32 v177, v199, v69
	ds_bpermute_b32 v178, v199, v101
	ds_bpermute_b32 v179, v199, v73
	ds_bpermute_b32 v180, v199, v105
	ds_bpermute_b32 v181, v199, v77
	ds_bpermute_b32 v182, v199, v109
	s_waitcnt lgkmcnt(0)
	v_cndmask_b32_e64 v216, v49, v167, s[40:41]
	v_cndmask_b32_e64 v217, v81, v168, s[40:41]
	v_cndmask_b32_e64 v218, v167, v49, s[40:41]
	v_cndmask_b32_e64 v219, v168, v81, s[40:41]
	v_fma_f32 v213, v12, v22, v216
	v_fma_f32 v214, v12, v23, v217
	v_fma_f32 v213, -v13, v23, v213
	v_fmac_f32_e32 v214, v13, v22
	v_fma_f32 v215, v12, v213, v218
	v_fma_f32 v248, v12, v214, v219
	v_fma_f32 v215, -v13, v214, v215
	v_fmac_f32_e32 v248, v13, v213
	v_cndmask_b32_e64 v183, v22, v213, s[40:41]
	v_cndmask_b32_e64 v184, v23, v214, s[40:41]
	v_cndmask_b32_e64 v224, v65, v175, s[40:41]
	v_cndmask_b32_e64 v225, v97, v176, s[40:41]
	v_cndmask_b32_e64 v226, v175, v65, s[40:41]
	v_cndmask_b32_e64 v227, v176, v97, s[40:41]
	v_fma_f32 v251, v20, v24, v224
	v_fma_f32 v252, v20, v25, v225
	v_fma_f32 v251, -v21, v25, v251
	v_fmac_f32_e32 v252, v21, v24
	v_fma_f32 v253, v20, v251, v226
	v_fma_f32 v211, v20, v252, v227
	v_fma_f32 v253, -v21, v252, v253
	v_fmac_f32_e32 v211, v21, v251
	v_cndmask_b32_e64 v191, v24, v251, s[40:41]
	v_cndmask_b32_e64 v192, v25, v252, s[40:41]
	v_cndmask_b32_e64 v216, v53, v169, s[40:41]
	v_cndmask_b32_e64 v217, v85, v170, s[40:41]
	v_cndmask_b32_e64 v218, v169, v53, s[40:41]
	v_cndmask_b32_e64 v219, v170, v85, s[40:41]
	v_fma_f32 v249, v12, v215, v216
	v_fma_f32 v250, v12, v248, v217
	v_fma_f32 v249, -v13, v248, v249
	v_fmac_f32_e32 v250, v13, v215
	v_fma_f32 v213, v12, v249, v218
	v_fma_f32 v214, v12, v250, v219
	v_fma_f32 v213, -v13, v250, v213
	v_fmac_f32_e32 v214, v13, v249
	v_cndmask_b32_e64 v185, v215, v249, s[40:41]
	v_cndmask_b32_e64 v186, v248, v250, s[40:41]
	v_cndmask_b32_e64 v224, v69, v177, s[40:41]
	v_cndmask_b32_e64 v225, v101, v178, s[40:41]
	v_cndmask_b32_e64 v226, v177, v69, s[40:41]
	v_cndmask_b32_e64 v227, v178, v101, s[40:41]
	v_fma_f32 v212, v20, v253, v224
	v_fma_f32 v209, v20, v211, v225
	v_fma_f32 v212, -v21, v211, v212
	v_fmac_f32_e32 v209, v21, v253
	v_fma_f32 v251, v20, v212, v226
	v_fma_f32 v252, v20, v209, v227
	v_fma_f32 v251, -v21, v209, v251
	v_fmac_f32_e32 v252, v21, v212
	v_cndmask_b32_e64 v193, v253, v212, s[40:41]
	v_cndmask_b32_e64 v194, v211, v209, s[40:41]
	v_cndmask_b32_e64 v216, v57, v171, s[40:41]
	v_cndmask_b32_e64 v217, v89, v172, s[40:41]
	v_cndmask_b32_e64 v218, v171, v57, s[40:41]
	v_cndmask_b32_e64 v219, v172, v89, s[40:41]
	v_fma_f32 v215, v12, v213, v216
	v_fma_f32 v248, v12, v214, v217
	v_fma_f32 v215, -v13, v214, v215
	v_fmac_f32_e32 v248, v13, v213
	v_fma_f32 v249, v12, v215, v218
	v_fma_f32 v250, v12, v248, v219
	v_fma_f32 v249, -v13, v248, v249
	v_fmac_f32_e32 v250, v13, v215
	v_cndmask_b32_e64 v187, v213, v215, s[40:41]
	v_cndmask_b32_e64 v188, v214, v248, s[40:41]
	v_cndmask_b32_e64 v224, v73, v179, s[40:41]
	v_cndmask_b32_e64 v225, v105, v180, s[40:41]
	v_cndmask_b32_e64 v226, v179, v73, s[40:41]
	v_cndmask_b32_e64 v227, v180, v105, s[40:41]
	v_fma_f32 v253, v20, v251, v224
	v_fma_f32 v211, v20, v252, v225
	v_fma_f32 v253, -v21, v252, v253
	v_fmac_f32_e32 v211, v21, v251
	v_fma_f32 v212, v20, v253, v226
	v_fma_f32 v209, v20, v211, v227
	v_fma_f32 v212, -v21, v211, v212
	v_fmac_f32_e32 v209, v21, v253
	v_cndmask_b32_e64 v195, v251, v253, s[40:41]
	v_cndmask_b32_e64 v196, v252, v211, s[40:41]
	v_cndmask_b32_e64 v216, v61, v173, s[40:41]
	v_cndmask_b32_e64 v217, v93, v174, s[40:41]
	v_cndmask_b32_e64 v218, v173, v61, s[40:41]
	v_cndmask_b32_e64 v219, v174, v93, s[40:41]
	v_fma_f32 v213, v12, v249, v216
	v_fma_f32 v214, v12, v250, v217
	v_fma_f32 v213, -v13, v250, v213
	v_fmac_f32_e32 v214, v13, v249
	v_fma_f32 v215, v12, v213, v218
	v_fma_f32 v248, v12, v214, v219
	v_fma_f32 v215, -v13, v214, v215
	v_fmac_f32_e32 v248, v13, v213
	v_cndmask_b32_e64 v189, v249, v213, s[40:41]
	v_cndmask_b32_e64 v190, v250, v214, s[40:41]
	v_cndmask_b32_e64 v224, v77, v181, s[40:41]
	v_cndmask_b32_e64 v225, v109, v182, s[40:41]
	v_cndmask_b32_e64 v226, v181, v77, s[40:41]
	v_cndmask_b32_e64 v227, v182, v109, s[40:41]
	v_fma_f32 v251, v20, v212, v224
	v_fma_f32 v252, v20, v209, v225
	v_fma_f32 v251, -v21, v209, v251
	v_fmac_f32_e32 v252, v21, v212
	v_fma_f32 v253, v20, v251, v226
	v_fma_f32 v211, v20, v252, v227
	v_fma_f32 v253, -v21, v252, v253
	v_fmac_f32_e32 v211, v21, v251
	v_cndmask_b32_e64 v197, v212, v251, s[40:41]
	v_cndmask_b32_e64 v198, v209, v252, s[40:41]
	v_mov_b32_e32 v22, v215
	v_mov_b32_e32 v23, v248
	v_mov_b32_e32 v24, v253
	v_mov_b32_e32 v25, v211
	v_fmac_f32_e32 v46, v6, v183
	v_fmac_f32_e32 v78, v6, v184
	v_fma_f32 v46, -v7, v184, v46
	v_fmac_f32_e32 v78, v7, v183
	v_fmac_f32_e32 v47, v8, v183
	v_fmac_f32_e32 v79, v8, v184
	v_fma_f32 v47, -v9, v184, v47
	v_fmac_f32_e32 v79, v9, v183
	v_fmac_f32_e32 v48, v10, v183
	v_fmac_f32_e32 v80, v10, v184
	v_fma_f32 v48, -v11, v184, v48
	v_fmac_f32_e32 v80, v11, v183
	v_fmac_f32_e32 v49, v12, v183
	v_fmac_f32_e32 v81, v12, v184
	v_fma_f32 v49, -v13, v184, v49
	v_fmac_f32_e32 v81, v13, v183
	v_fmac_f32_e32 v50, v6, v185
	v_fmac_f32_e32 v82, v6, v186
	v_fma_f32 v50, -v7, v186, v50
	v_fmac_f32_e32 v82, v7, v185
	v_fmac_f32_e32 v51, v8, v185
	v_fmac_f32_e32 v83, v8, v186
	v_fma_f32 v51, -v9, v186, v51
	v_fmac_f32_e32 v83, v9, v185
	v_fmac_f32_e32 v52, v10, v185
	v_fmac_f32_e32 v84, v10, v186
	v_fma_f32 v52, -v11, v186, v52
	v_fmac_f32_e32 v84, v11, v185
	v_fmac_f32_e32 v53, v12, v185
	v_fmac_f32_e32 v85, v12, v186
	v_fma_f32 v53, -v13, v186, v53
	v_fmac_f32_e32 v85, v13, v185
	v_fmac_f32_e32 v54, v6, v187
	v_fmac_f32_e32 v86, v6, v188
	v_fma_f32 v54, -v7, v188, v54
	v_fmac_f32_e32 v86, v7, v187
	v_fmac_f32_e32 v55, v8, v187
	v_fmac_f32_e32 v87, v8, v188
	v_fma_f32 v55, -v9, v188, v55
	v_fmac_f32_e32 v87, v9, v187
	v_fmac_f32_e32 v56, v10, v187
	v_fmac_f32_e32 v88, v10, v188
	v_fma_f32 v56, -v11, v188, v56
	v_fmac_f32_e32 v88, v11, v187
	v_fmac_f32_e32 v57, v12, v187
	v_fmac_f32_e32 v89, v12, v188
	v_fma_f32 v57, -v13, v188, v57
	v_fmac_f32_e32 v89, v13, v187
	v_fmac_f32_e32 v58, v6, v189
	v_fmac_f32_e32 v90, v6, v190
	v_fma_f32 v58, -v7, v190, v58
	v_fmac_f32_e32 v90, v7, v189
	v_fmac_f32_e32 v59, v8, v189
	v_fmac_f32_e32 v91, v8, v190
	v_fma_f32 v59, -v9, v190, v59
	v_fmac_f32_e32 v91, v9, v189
	v_fmac_f32_e32 v60, v10, v189
	v_fmac_f32_e32 v92, v10, v190
	v_fma_f32 v60, -v11, v190, v60
	v_fmac_f32_e32 v92, v11, v189
	v_fmac_f32_e32 v61, v12, v189
	v_fmac_f32_e32 v93, v12, v190
	v_fma_f32 v61, -v13, v190, v61
	v_fmac_f32_e32 v93, v13, v189
	v_fmac_f32_e32 v62, v14, v191
	v_fmac_f32_e32 v94, v14, v192
	v_fma_f32 v62, -v15, v192, v62
	v_fmac_f32_e32 v94, v15, v191
	v_fmac_f32_e32 v63, v16, v191
	v_fmac_f32_e32 v95, v16, v192
	v_fma_f32 v63, -v17, v192, v63
	v_fmac_f32_e32 v95, v17, v191
	v_fmac_f32_e32 v64, v18, v191
	v_fmac_f32_e32 v96, v18, v192
	v_fma_f32 v64, -v19, v192, v64
	v_fmac_f32_e32 v96, v19, v191
	v_fmac_f32_e32 v65, v20, v191
	v_fmac_f32_e32 v97, v20, v192
	v_fma_f32 v65, -v21, v192, v65
	v_fmac_f32_e32 v97, v21, v191
	v_fmac_f32_e32 v66, v14, v193
	v_fmac_f32_e32 v98, v14, v194
	v_fma_f32 v66, -v15, v194, v66
	v_fmac_f32_e32 v98, v15, v193
	v_fmac_f32_e32 v67, v16, v193
	v_fmac_f32_e32 v99, v16, v194
	v_fma_f32 v67, -v17, v194, v67
	v_fmac_f32_e32 v99, v17, v193
	v_fmac_f32_e32 v68, v18, v193
	v_fmac_f32_e32 v100, v18, v194
	v_fma_f32 v68, -v19, v194, v68
	v_fmac_f32_e32 v100, v19, v193
	v_fmac_f32_e32 v69, v20, v193
	v_fmac_f32_e32 v101, v20, v194
	v_fma_f32 v69, -v21, v194, v69
	v_fmac_f32_e32 v101, v21, v193
	v_fmac_f32_e32 v70, v14, v195
	v_fmac_f32_e32 v102, v14, v196
	v_fma_f32 v70, -v15, v196, v70
	v_fmac_f32_e32 v102, v15, v195
	v_fmac_f32_e32 v71, v16, v195
	v_fmac_f32_e32 v103, v16, v196
	v_fma_f32 v71, -v17, v196, v71
	v_fmac_f32_e32 v103, v17, v195
	v_fmac_f32_e32 v72, v18, v195
	v_fmac_f32_e32 v104, v18, v196
	v_fma_f32 v72, -v19, v196, v72
	v_fmac_f32_e32 v104, v19, v195
	v_fmac_f32_e32 v73, v20, v195
	v_fmac_f32_e32 v105, v20, v196
	v_fma_f32 v73, -v21, v196, v73
	v_fmac_f32_e32 v105, v21, v195
	v_fmac_f32_e32 v74, v14, v197
	v_fmac_f32_e32 v106, v14, v198
	v_fma_f32 v74, -v15, v198, v74
	v_fmac_f32_e32 v106, v15, v197
	v_fmac_f32_e32 v75, v16, v197
	v_fmac_f32_e32 v107, v16, v198
	v_fma_f32 v75, -v17, v198, v75
	v_fmac_f32_e32 v107, v17, v197
	v_fmac_f32_e32 v76, v18, v197
	v_fmac_f32_e32 v108, v18, v198
	v_fma_f32 v76, -v19, v198, v76
	v_fmac_f32_e32 v108, v19, v197
	v_fmac_f32_e32 v77, v20, v197
	v_fmac_f32_e32 v109, v20, v198
	v_fma_f32 v77, -v21, v198, v77
	v_fmac_f32_e32 v109, v21, v197
	v_cvt_pk_bf16_f32 v216, v46, v47
	v_cvt_pk_bf16_f32 v217, v48, v49
	ds_write_b64 v200, v[216:217] offset:0
	v_cvt_pk_bf16_f32 v218, v50, v51
	v_cvt_pk_bf16_f32 v219, v52, v53
	ds_write_b64 v200, v[218:219] offset:16
	v_cvt_pk_bf16_f32 v220, v54, v55
	v_cvt_pk_bf16_f32 v221, v56, v57
	ds_write_b64 v200, v[220:221] offset:32
	v_cvt_pk_bf16_f32 v222, v58, v59
	v_cvt_pk_bf16_f32 v223, v60, v61
	ds_write_b64 v200, v[222:223] offset:48
	v_cvt_pk_bf16_f32 v224, v62, v63
	v_cvt_pk_bf16_f32 v225, v64, v65
	ds_write_b64 v200, v[224:225] offset:2304
	v_cvt_pk_bf16_f32 v226, v66, v67
	v_cvt_pk_bf16_f32 v227, v68, v69
	ds_write_b64 v200, v[226:227] offset:2320
	v_cvt_pk_bf16_f32 v228, v70, v71
	v_cvt_pk_bf16_f32 v229, v72, v73
	ds_write_b64 v200, v[228:229] offset:2336
	v_cvt_pk_bf16_f32 v230, v74, v75
	v_cvt_pk_bf16_f32 v231, v76, v77
	ds_write_b64 v200, v[230:231] offset:2352
	v_cvt_pk_bf16_f32 v232, v78, v79
	v_cvt_pk_bf16_f32 v233, v80, v81
	ds_write_b64 v200, v[232:233] offset:4608
	v_cvt_pk_bf16_f32 v234, v82, v83
	v_cvt_pk_bf16_f32 v235, v84, v85
	ds_write_b64 v200, v[234:235] offset:4624
	v_cvt_pk_bf16_f32 v236, v86, v87
	v_cvt_pk_bf16_f32 v237, v88, v89
	ds_write_b64 v200, v[236:237] offset:4640
	v_cvt_pk_bf16_f32 v238, v90, v91
	v_cvt_pk_bf16_f32 v239, v92, v93
	ds_write_b64 v200, v[238:239] offset:4656
	v_cvt_pk_bf16_f32 v240, v94, v95
	v_cvt_pk_bf16_f32 v241, v96, v97
	ds_write_b64 v200, v[240:241] offset:6912
	v_cvt_pk_bf16_f32 v242, v98, v99
	v_cvt_pk_bf16_f32 v243, v100, v101
	ds_write_b64 v200, v[242:243] offset:6928
	v_cvt_pk_bf16_f32 v244, v102, v103
	v_cvt_pk_bf16_f32 v245, v104, v105
	ds_write_b64 v200, v[244:245] offset:6944
	v_cvt_pk_bf16_f32 v246, v106, v107
	v_cvt_pk_bf16_f32 v247, v108, v109
	ds_write_b64 v200, v[246:247] offset:6960
	s_waitcnt lgkmcnt(0)
	ds_read_b64_tr_b16 v[216:217], v201 offset:0
	ds_read_b64_tr_b16 v[218:219], v201 offset:288
	ds_read_b64_tr_b16 v[220:221], v201 offset:1152
	ds_read_b64_tr_b16 v[222:223], v201 offset:1440
	ds_read_b64_tr_b16 v[224:225], v201 offset:2304
	ds_read_b64_tr_b16 v[226:227], v201 offset:2592
	ds_read_b64_tr_b16 v[228:229], v201 offset:3456
	ds_read_b64_tr_b16 v[230:231], v201 offset:3744
	ds_read_b64_tr_b16 v[232:233], v201 offset:4608
	ds_read_b64_tr_b16 v[234:235], v201 offset:4896
	ds_read_b64_tr_b16 v[236:237], v201 offset:5760
	ds_read_b64_tr_b16 v[238:239], v201 offset:6048
	ds_read_b64_tr_b16 v[240:241], v201 offset:6912
	ds_read_b64_tr_b16 v[242:243], v201 offset:7200
	ds_read_b64_tr_b16 v[244:245], v201 offset:8064
	ds_read_b64_tr_b16 v[246:247], v201 offset:8352
	s_waitcnt lgkmcnt(14)
	v_mfma_f32_32x32x16_bf16 v[110:125], v[216:219], v[134:137], v[110:125]
	s_waitcnt lgkmcnt(12)
	v_mfma_f32_32x32x16_bf16 v[110:125], v[220:223], v[138:141], v[110:125]
	s_waitcnt lgkmcnt(10)
	v_mfma_f32_32x32x16_bf16 v[110:125], v[224:227], v[142:145], v[110:125]
	s_waitcnt lgkmcnt(8)
	v_mfma_f32_32x32x16_bf16 v[110:125], v[228:231], v[146:149], v[110:125]
	s_waitcnt lgkmcnt(6)
	v_mfma_f32_32x32x16_bf16 v[110:125], v[232:235], v[150:153], v[110:125]
	s_waitcnt lgkmcnt(4)
	v_mfma_f32_32x32x16_bf16 v[110:125], v[236:239], v[154:157], v[110:125]
	s_waitcnt lgkmcnt(2)
	v_mfma_f32_32x32x16_bf16 v[110:125], v[240:243], v[158:161], v[110:125]
	s_waitcnt lgkmcnt(0)
	v_mfma_f32_32x32x16_bf16 v[110:125], v[244:247], v[162:165], v[110:125]
	s_nop 7
	s_nop 3
	s_mov_b64 exec, s[44:45]
	ds_write_b32 v202, v110 offset:0
	ds_write_b32 v202, v111 offset:64
	ds_write_b32 v202, v112 offset:128
	ds_write_b32 v202, v113 offset:192
	ds_write_b32 v202, v114 offset:512
	ds_write_b32 v202, v115 offset:576
	ds_write_b32 v202, v116 offset:640
	ds_write_b32 v202, v117 offset:704
	ds_write_b32 v202, v118 offset:1024
	ds_write_b32 v202, v119 offset:1088
	ds_write_b32 v202, v120 offset:1152
	ds_write_b32 v202, v121 offset:1216
	ds_write_b32 v202, v122 offset:1536
	ds_write_b32 v202, v123 offset:1600
	ds_write_b32 v202, v124 offset:1664
	ds_write_b32 v202, v125 offset:1728
	s_mov_b64 exec, -1
	s_waitcnt lgkmcnt(0)
	ds_read_b128 v[216:219], v203
	ds_read_b128 v[220:223], v203 offset:16
	s_waitcnt lgkmcnt(0)
	v_mul_f32_e32 v224, 0x3d372713, v216
	v_mul_f32_e32 v225, 0x3d372713, v217
	v_mul_f32_e32 v226, 0x3d372713, v218
	v_mul_f32_e32 v227, 0x3d372713, v219
	v_mul_f32_e32 v228, 0x3d372713, v220
	v_mul_f32_e32 v229, 0x3d372713, v221
	v_mul_f32_e32 v230, 0x3d372713, v222
	v_mul_f32_e32 v231, 0x3d372713, v223
	v_mul_f32_e32 v224, v216, v224
	v_mul_f32_e32 v225, v217, v225
	v_mul_f32_e32 v226, v218, v226
	v_mul_f32_e32 v227, v219, v227
	v_mul_f32_e32 v228, v220, v228
	v_mul_f32_e32 v229, v221, v229
	v_mul_f32_e32 v230, v222, v230
	v_mul_f32_e32 v231, v223, v231
	v_fma_f32 v224, v216, v224, v216
	v_fma_f32 v225, v217, v225, v217
	v_fma_f32 v226, v218, v226, v218
	v_fma_f32 v227, v219, v227, v219
	v_fma_f32 v228, v220, v228, v220
	v_fma_f32 v229, v221, v229, v221
	v_fma_f32 v230, v222, v230, v222
	v_fma_f32 v231, v223, v231, v223
	v_mul_f32_e32 v224, 0x3f4c422a, v224
	v_mul_f32_e32 v225, 0x3f4c422a, v225
	v_mul_f32_e32 v226, 0x3f4c422a, v226
	v_mul_f32_e32 v227, 0x3f4c422a, v227
	v_mul_f32_e32 v228, 0x3f4c422a, v228
	v_mul_f32_e32 v229, 0x3f4c422a, v229
	v_mul_f32_e32 v230, 0x3f4c422a, v230
	v_mul_f32_e32 v231, 0x3f4c422a, v231
	v_add_f32_e32 v224, v224, v224
	v_add_f32_e32 v225, v225, v225
	v_add_f32_e32 v226, v226, v226
	v_add_f32_e32 v227, v227, v227
	v_add_f32_e32 v228, v228, v228
	v_add_f32_e32 v229, v229, v229
	v_add_f32_e32 v230, v230, v230
	v_add_f32_e32 v231, v231, v231
	v_mul_f32_e32 v224, 0xbfb8aa3b, v224
	v_mul_f32_e32 v225, 0xbfb8aa3b, v225
	v_mul_f32_e32 v226, 0xbfb8aa3b, v226
	v_mul_f32_e32 v227, 0xbfb8aa3b, v227
	v_mul_f32_e32 v228, 0xbfb8aa3b, v228
	v_mul_f32_e32 v229, 0xbfb8aa3b, v229
	v_mul_f32_e32 v230, 0xbfb8aa3b, v230
	v_mul_f32_e32 v231, 0xbfb8aa3b, v231
	v_exp_f32_e32 v224, v224
	v_exp_f32_e32 v225, v225
	v_exp_f32_e32 v226, v226
	v_exp_f32_e32 v227, v227
	v_exp_f32_e32 v228, v228
	v_exp_f32_e32 v229, v229
	v_exp_f32_e32 v230, v230
	v_exp_f32_e32 v231, v231
	s_nop 0
	v_add_f32_e32 v224, 1.0, v224
	v_add_f32_e32 v225, 1.0, v225
	v_add_f32_e32 v226, 1.0, v226
	v_add_f32_e32 v227, 1.0, v227
	v_add_f32_e32 v228, 1.0, v228
	v_add_f32_e32 v229, 1.0, v229
	v_add_f32_e32 v230, 1.0, v230
	v_add_f32_e32 v231, 1.0, v231
	v_rcp_f32_e32 v224, v224
	v_rcp_f32_e32 v225, v225
	v_rcp_f32_e32 v226, v226
	v_rcp_f32_e32 v227, v227
	v_rcp_f32_e32 v228, v228
	v_rcp_f32_e32 v229, v229
	v_rcp_f32_e32 v230, v230
	v_rcp_f32_e32 v231, v231
	s_nop 0
	v_mul_f32_e32 v224, v216, v224
	v_mul_f32_e32 v225, v217, v225
	v_mul_f32_e32 v226, v218, v226
	v_mul_f32_e32 v227, v219, v227
	v_mul_f32_e32 v228, v220, v228
	v_mul_f32_e32 v229, v221, v229
	v_mul_f32_e32 v230, v222, v230
	v_mul_f32_e32 v231, v223, v231
	v_cvt_pk_bf16_f32 v232, v224, v225
	v_cvt_pk_bf16_f32 v233, v226, v227
	v_cvt_pk_bf16_f32 v234, v228, v229
	v_cvt_pk_bf16_f32 v235, v230, v231
	s_add_u32 s70, s60, 0x60000
	s_addc_u32 s71, s61, 0
	global_store_dwordx4 v205, v[232:235], s[70:71]
	s_cmp_eq_u32 s15, 31
	s_cbranch_scc0 .Lpc_nofin
	s_mov_b64 exec, s[42:43]
	global_store_dword v206, v22, s[64:65]
	global_store_dword v206, v24, s[64:65] offset:128
	global_store_dword v206, v23, s[66:67]
	global_store_dword v206, v25, s[66:67] offset:128
	s_mov_b64 exec, -1
